# v109 + stacked: P8 and P9 epilogue stores via ds_bpermute (quad-contiguous), P1 first-iteration vmcnt(24) after the plain epilogue
# speedup vs baseline: 1.0084x; 1.0034x over previous
; #define PG8_STAGE(bufoff, gbase, voff) do { _Pragma("unroll") for (int _i = 0; _i < 2; ++_i) \
;         __builtin_amdgcn_global_load_lds((const unsigned*)((const char*)(gbase) + (voff)[_i]), (PG8_LAS unsigned*)(lds + (bufoff) + ldsw + _i * 8192), 16, 0, 0); } while (0)
; #define PG8_WAIT_V(n) asm volatile("s_waitcnt vmcnt(" #n ")" ::: "memory")
; #define PG8_BAR __builtin_amdgcn_s_barrier()
; template <class Epi, class Sched, bool ALIGN_EPI = false, bool SP2 = false>
; __device__ __forceinline__ void gemm_phase(PG8_LAS unsigned char* lds, const Gemm g, const Sched& S, const Epi& E) {
;     ...
;     for (int i = 0; i < 2; ++i) { int R, C; stage_rc(tid * 16 + i * 8192, R, C); const int Rb = Epi::PERM ? ((R & ~31) + perm32(R & 31)) : R;
;         voffA[i] = (unsigned)(R * K + C) * 2u; voffB[i] = (unsigned)(Rb * K + C) * 2u; }
;     const size_t kstep = (size_t)(BK * 2);
;     const size_t hstep = (size_t)HALF * K * 2;
;     const size_t tstep = 2 * hstep;
;     const unsigned ldsw = (unsigned)wid * 1024u;
;     const int aoff = lds_byte(wr * 64 + fr, fq * 8), boff = lds_byte(wc * 32 + fr, fq * 8);
;     ...
;     Unit cur, nxt; int ui = 0;
;     if (!S.next(0, cur)) return;
;     f32x4 acc[2][2][4][2];
; #pragma unroll
;     for (int a = 0; a < 2; ++a)
; #pragma unroll
;         for (int b = 0; b < 2; ++b)
; #pragma unroll
;             for (int m = 0; m < 4; ++m)
; #pragma unroll
;                 for (int n = 0; n < 2; ++n) acc[a][b][m][n] = (f32x4){0.f, 0.f, 0.f, 0.f};
;     bf16x8 At[4][2], B0[2][2], B1[2][2];
;     const char* cA = (const char*)g.A + (size_t)cur.pm * tstep; const char* cB = (const char*)g.Bt + (size_t)cur.pn * tstep;
;     S.a_ready(cur);
;     if constexpr (SP2) {
;         PG8_STAGE(PG8_SB(0, 0), cB, voffB); PG8_STAGE(PG8_SB(0, 1), cB + hstep, voffB); PG8_STAGE(PG8_SA(0, 0), cA, voffA); PG8_STAGE(PG8_SA(0, 1), cA + hstep, voffA);
;         if (wr == 1) PG8_BAR;
;         PG8_WAIT_V(2); PG8_BAR;
.LBB0_171:
	s_andn2_b64 vcc, exec, s[0:1]
	s_cbranch_vccnz .LBB0_223
	v_lshrrev_b32_e32 v4, 1, v0
	v_lshrrev_b32_e32 v5, 5, v0
	v_lshlrev_b32_e32 v2, 4, v0
	v_and_b32_e32 v3, 32, v0
	v_and_b32_e32 v4, 24, v4
	v_and_b32_e32 v5, 4, v5
	v_bfe_u32 v6, v0, 2, 2
	v_bfe_u32 v12, v0, 2, 4
	v_bitop3_b32 v10, v2, v3, 48 bitop3:0x6c
	v_and_b32_e32 v11, 64, v0
	v_or3_b32 v4, v5, v6, v4
	v_lshrrev_b32_e32 v5, 3, v0
	v_or_b32_e32 v13, 0x2000, v2
	v_or_b32_e32 v3, v10, v11
	v_and_or_b32 v6, v5, 48, v12
	v_and_or_b32 v5, v5, 32, v4
	v_lshrrev_b32_e32 v2, 7, v13
	s_movk_i32 s0, 0x70
	s_lshr_b32 s1, s4, 6
	v_lshl_or_b32 v140, v5, 13, v3
	v_and_or_b32 v5, v2, s0, v12
	s_movk_i32 s0, 0x60
	s_ashr_i32 s31, s30, 31
	s_ashr_i32 s7, s6, 31
	v_and_or_b32 v2, v2, s0, v4
	s_lshr_b32 s0, s4, 8
	s_lshl_b32 s33, s1, 10
	s_lshl_b64 s[2:3], s[30:31], 21
	s_lshl_b64 s[10:11], s[6:7], 21
	s_add_u32 s36, s78, s10
	s_addc_u32 s37, s79, s11
	s_add_i32 s40, s33, 0
	s_add_i32 m0, s40, 0x10000
	v_lshl_or_b32 v144, v2, 13, v3
	global_load_lds_dwordx4 v140, s[36:37]
	s_add_i32 m0, s40, 0x12000
	s_add_u32 s10, s36, 0x100000
	global_load_lds_dwordx4 v144, s[36:37]
	s_addc_u32 s11, s37, 0
	s_add_i32 m0, s40, 0x14000
	v_lshl_or_b32 v138, v6, 13, v3
	global_load_lds_dwordx4 v140, s[10:11]
	s_add_i32 m0, s40, 0x16000
	s_add_u32 s34, s84, s2
	s_addc_u32 s35, s85, s3
	s_add_i32 s41, s40, 0x2000
	global_load_lds_dwordx4 v144, s[10:11]
	s_mov_b32 m0, s40
	s_add_u32 s2, s34, 0x100000
	v_lshl_or_b32 v142, v5, 13, v3
	global_load_lds_dwordx4 v138, s[34:35]
	s_mov_b32 m0, s41
	s_addc_u32 s3, s35, 0
	s_add_i32 s42, s40, 0x4000
	global_load_lds_dwordx4 v142, s[34:35]
	s_mov_b32 m0, s42
	s_add_i32 s43, s40, 0x6000
	global_load_lds_dwordx4 v138, s[2:3]
	s_mov_b32 m0, s43
	v_mov_b32_e32 v147, 0
	global_load_lds_dwordx4 v142, s[2:3]
	v_mov_b32_e32 v141, v147
	v_mov_b32_e32 v145, v147
	v_mov_b32_e32 v139, v147
	v_mov_b32_e32 v143, v147
	s_cmp_eq_u32 s0, 1
	s_mov_b32 s44, 0
	s_mov_b32 s32, 0
	v_lshl_add_u64 v[8:9], s[36:37], 0, v[140:141]
	v_lshl_add_u64 v[6:7], s[36:37], 0, v[144:145]
	v_lshl_add_u64 v[2:3], s[34:35], 0, v[138:139]
	s_cselect_b64 s[2:3], -1, 0
	s_cmp_lg_u32 s0, 1
	v_lshl_add_u64 v[4:5], s[34:35], 0, v[142:143]
	s_cbranch_scc1 .LBB0_174
	s_barrier

; #define PG8_STAGE(bufoff, gbase, voff) do { _Pragma("unroll") for (int _i = 0; _i < 2; ++_i) \
;         __builtin_amdgcn_global_load_lds((const unsigned*)((const char*)(gbase) + (voff)[_i]), (PG8_LAS unsigned*)(lds + (bufoff) + ldsw + _i * 8192), 16, 0, 0); } while (0)
; #define PG8_LDA(dst, b, h) do { _Pragma("unroll") for (int m = 0; m < 4; ++m) _Pragma("unroll") for (int k = 0; k < 2; ++k) dst[m][k] = *(const PG8_LAS bf16x8*)(lds + PG8_SA(b, h) + aoff + m * 2048 + k * 1024); } while (0)
; #define PG8_LDB(dst, b, h) do { _Pragma("unroll") for (int n = 0; n < 2; ++n) _Pragma("unroll") for (int k = 0; k < 2; ++k) dst[n][k] = *(const PG8_LAS bf16x8*)(lds + PG8_SB(b, h) + boff + n * 2048 + k * 1024); } while (0)
; #define PG8_MMA(ai, bj, At, Bt) do { __builtin_amdgcn_s_setprio(1); _Pragma("unroll") for (int m = 0; m < 4; ++m) _Pragma("unroll") for (int n = 0; n < 2; ++n) _Pragma("unroll") for (int k = 0; k < 2; ++k) \
;         acc[ai][bj][m][n] = __builtin_amdgcn_mfma_f32_16x16x32_bf16(Bt[n][k], At[m][k], acc[ai][bj][m][n], 0, 0, 0); __builtin_amdgcn_s_setprio(0); } while (0)
; #define PG8_WAIT_V(n) asm volatile("s_waitcnt vmcnt(" #n ")" ::: "memory")
; #define PG8_WAIT_L(n) asm volatile("s_waitcnt lgkmcnt(" #n ")" ::: "memory")
; #define PG8_BAR __builtin_amdgcn_s_barrier()
; #define PG8_SCHED __builtin_amdgcn_sched_barrier(0)
; template <class Epi, class Sched, bool ALIGN_EPI = false, bool SP2 = false>
; __device__ __forceinline__ void gemm_phase(PG8_LAS unsigned char* lds, const Gemm g, const Sched& S, const Epi& E) {
;     ...
;         for (int t = 0; t < nt; t += 2) {
;             const bool last = (t == nt - 2);
;             const char* a1 = cA + (size_t)(t + 1) * kstep;
;             const char* a2 = last ? nA : cA + (size_t)(t + 2) * kstep; const char* b2 = last ? nB : cB + (size_t)(t + 2) * kstep;
;             const char* a3 = a2 + kstep; const char* b3 = b2 + kstep;
;             if (last && has_next) S.a_ready(nxt);
;             if constexpr (SP2) {
;             PG8_LDB(B0, 0, 0); PG8_LDB(B1, 0, 1); PG8_SCHED; PG8_LDA(At, 0, 0); PG8_STAGE(PG8_SA(1, 1), a1 + hstep, voffA);
;             PG8_WAIT_V(8); PG8_WAIT_L(0); PG8_BAR; PG8_MMA(0, 0, At, B0); PG8_MMA(0, 1, At, B1); PG8_BAR; PG8_SCHED;
.LBB0_180:
	s_add_u32 s36, s34, 0xfff00000
	s_addc_u32 s37, s35, -1
	s_mov_b32 m0, s45
	s_nop 0
	global_load_lds_dwordx4 v138, s[36:37]
	s_mov_b32 m0, s46
	s_nop 0
	global_load_lds_dwordx4 v142, s[36:37]
	s_add_u32 s36, s36, 0x80
	s_addc_u32 s37, s37, 0
	ds_read_b128 v[130:133], v170
	ds_read_b128 v[134:137], v170 offset:1024
	ds_read_b128 v[178:181], v170 offset:2048
	ds_read_b128 v[182:185], v170 offset:3072
	ds_read_b128 v[186:189], v171
	ds_read_b128 v[190:193], v171 offset:1024
	ds_read_b128 v[194:197], v171 offset:2048
	ds_read_b128 v[200:203], v171 offset:3072
	s_cmp_eq_u32 s56, 60
	s_cselect_b32 s39, s7, s37
	s_cselect_b32 s38, s25, s36
	s_cselect_b32 s37, s15, s55
	s_cselect_b32 s36, s31, s54
	s_add_i32 m0, s40, 0xc000
	ds_read_b128 v[204:207], v172
	ds_read_b128 v[208:211], v172 offset:1024
	ds_read_b128 v[212:215], v172 offset:2048
	ds_read_b128 v[216:219], v172 offset:3072
	ds_read_b128 v[220:223], v172 offset:4096
	ds_read_b128 v[224:227], v172 offset:5120
	ds_read_b128 v[228:231], v172 offset:6144
	ds_read_b128 v[232:235], v172 offset:7168
	global_load_lds_dwordx4 v148, s[34:35]
	s_add_i32 m0, s40, 0xe000
	s_nop 0
	global_load_lds_dwordx4 v150, s[34:35]
	s_cmp_eq_u32 s56, -2
	s_cbranch_scc0 .Lrw_strict
	s_cmp_eq_u32 s32, 1
	s_cbranch_scc0 .Lrw_strict
	s_waitcnt vmcnt(24)
	s_branch .Lrw_done

; #define PG8_STAGE(bufoff, gbase, voff) do { _Pragma("unroll") for (int _i = 0; _i < 2; ++_i) \
;         __builtin_amdgcn_global_load_lds((const unsigned*)((const char*)(gbase) + (voff)[_i]), (PG8_LAS unsigned*)(lds + (bufoff) + ldsw + _i * 8192), 16, 0, 0); } while (0)
; #define PG8_LDA(dst, b, h) do { _Pragma("unroll") for (int m = 0; m < 4; ++m) _Pragma("unroll") for (int k = 0; k < 2; ++k) dst[m][k] = *(const PG8_LAS bf16x8*)(lds + PG8_SA(b, h) + aoff + m * 2048 + k * 1024); } while (0)
; #define PG8_LDB(dst, b, h) do { _Pragma("unroll") for (int n = 0; n < 2; ++n) _Pragma("unroll") for (int k = 0; k < 2; ++k) dst[n][k] = *(const PG8_LAS bf16x8*)(lds + PG8_SB(b, h) + boff + n * 2048 + k * 1024); } while (0)
; #define PG8_MMA(ai, bj, At, Bt) do { __builtin_amdgcn_s_setprio(1); _Pragma("unroll") for (int m = 0; m < 4; ++m) _Pragma("unroll") for (int n = 0; n < 2; ++n) _Pragma("unroll") for (int k = 0; k < 2; ++k) \
;         acc[ai][bj][m][n] = __builtin_amdgcn_mfma_f32_16x16x32_bf16(Bt[n][k], At[m][k], acc[ai][bj][m][n], 0, 0, 0); __builtin_amdgcn_s_setprio(0); } while (0)
; #define PG8_WAIT_V(n) asm volatile("s_waitcnt vmcnt(" #n ")" ::: "memory")
; #define PG8_WAIT_L(n) asm volatile("s_waitcnt lgkmcnt(" #n ")" ::: "memory")
; #define PG8_BAR __builtin_amdgcn_s_barrier()
; #define PG8_SCHED __builtin_amdgcn_sched_barrier(0)
; template <class Epi, class Sched, bool ALIGN_EPI = false, bool SP2 = false>
; __device__ __forceinline__ void gemm_phase(PG8_LAS unsigned char* lds, const Gemm g, const Sched& S, const Epi& E) {
;     ...
;             PG8_LDB(B0, 0, 0); PG8_LDB(B1, 0, 1); PG8_SCHED; PG8_LDA(At, 0, 0); PG8_STAGE(PG8_SA(1, 1), a1 + hstep, voffA);
;             PG8_WAIT_V(8); PG8_WAIT_L(0); PG8_BAR; PG8_MMA(0, 0, At, B0); PG8_MMA(0, 1, At, B1); PG8_BAR; PG8_SCHED;
;             PG8_LDA(At, 0, 1); PG8_STAGE(PG8_SB(0, 0), b2, voffB); PG8_STAGE(PG8_SB(0, 1), b2 + hstep, voffB); PG8_STAGE(PG8_SA(0, 0), a2, voffA);
;             PG8_WAIT_V(8); PG8_WAIT_L(0); PG8_BAR; PG8_MMA(1, 0, At, B0); PG8_MMA(1, 1, At, B1); PG8_BAR; PG8_SCHED;
.Lrw_done:
	s_waitcnt lgkmcnt(0)
	s_setprio 1
	s_barrier
	v_mfma_f32_16x16x32_bf16 v[126:129], v[130:133], v[204:207], v[126:129]
	v_mfma_f32_16x16x32_bf16 v[122:125], v[178:181], v[204:207], v[122:125]
	v_mfma_f32_16x16x32_bf16 v[110:113], v[130:133], v[212:215], v[110:113]
	v_mfma_f32_16x16x32_bf16 v[106:109], v[178:181], v[212:215], v[106:109]
	v_mfma_f32_16x16x32_bf16 v[94:97], v[130:133], v[220:223], v[94:97]
	v_mfma_f32_16x16x32_bf16 v[90:93], v[178:181], v[220:223], v[90:93]
	v_mfma_f32_16x16x32_bf16 v[78:81], v[130:133], v[228:231], v[78:81]
	v_mfma_f32_16x16x32_bf16 v[74:77], v[178:181], v[228:231], v[74:77]
	v_mfma_f32_16x16x32_bf16 v[126:129], v[134:137], v[208:211], v[126:129]
	v_mfma_f32_16x16x32_bf16 v[122:125], v[182:185], v[208:211], v[122:125]
	v_mfma_f32_16x16x32_bf16 v[110:113], v[134:137], v[216:219], v[110:113]
	v_mfma_f32_16x16x32_bf16 v[106:109], v[182:185], v[216:219], v[106:109]
	v_mfma_f32_16x16x32_bf16 v[94:97], v[134:137], v[224:227], v[94:97]
	v_mfma_f32_16x16x32_bf16 v[90:93], v[182:185], v[224:227], v[90:93]
	v_mfma_f32_16x16x32_bf16 v[78:81], v[134:137], v[232:235], v[78:81]
	v_mfma_f32_16x16x32_bf16 v[74:77], v[182:185], v[232:235], v[74:77]
	v_mfma_f32_16x16x32_bf16 v[118:121], v[186:189], v[204:207], v[118:121]
	v_mfma_f32_16x16x32_bf16 v[114:117], v[194:197], v[204:207], v[114:117]
	v_mfma_f32_16x16x32_bf16 v[102:105], v[186:189], v[212:215], v[102:105]
	v_mfma_f32_16x16x32_bf16 v[98:101], v[194:197], v[212:215], v[98:101]
	v_mfma_f32_16x16x32_bf16 v[86:89], v[186:189], v[220:223], v[86:89]
	v_mfma_f32_16x16x32_bf16 v[82:85], v[194:197], v[220:223], v[82:85]
	v_mfma_f32_16x16x32_bf16 v[70:73], v[186:189], v[228:231], v[70:73]
	v_mfma_f32_16x16x32_bf16 v[66:69], v[194:197], v[228:231], v[66:69]
	v_mfma_f32_16x16x32_bf16 v[118:121], v[190:193], v[208:211], v[118:121]
	v_mfma_f32_16x16x32_bf16 v[114:117], v[200:203], v[208:211], v[114:117]
	v_mfma_f32_16x16x32_bf16 v[102:105], v[190:193], v[216:219], v[102:105]
	v_mfma_f32_16x16x32_bf16 v[98:101], v[200:203], v[216:219], v[98:101]
	v_mfma_f32_16x16x32_bf16 v[86:89], v[190:193], v[224:227], v[86:89]
	v_mfma_f32_16x16x32_bf16 v[82:85], v[200:203], v[224:227], v[82:85]
	v_mfma_f32_16x16x32_bf16 v[70:73], v[190:193], v[232:235], v[70:73]
	v_mfma_f32_16x16x32_bf16 v[66:69], v[200:203], v[232:235], v[66:69]
	s_barrier
	s_setprio 0
	s_add_i32 s57, s49, s33
	s_mov_b32 m0, s57
	ds_read_b128 v[204:207], v172 offset:16384
	ds_read_b128 v[208:211], v172 offset:17408
	ds_read_b128 v[212:215], v172 offset:18432
	ds_read_b128 v[216:219], v172 offset:19456
	ds_read_b128 v[220:223], v172 offset:20480
	ds_read_b128 v[224:227], v172 offset:21504
	ds_read_b128 v[228:231], v172 offset:22528
	ds_read_b128 v[232:235], v172 offset:23552
	global_load_lds_dwordx4 v140, s[36:37]
	s_add_i32 m0, s57, 0x2000
	s_add_u32 s58, s36, 0x100000
	s_addc_u32 s59, s37, 0
	s_add_i32 s57, s50, s33
	global_load_lds_dwordx4 v144, s[36:37]
	s_mov_b32 m0, s57
	s_nop 0
	global_load_lds_dwordx4 v140, s[58:59]
	s_add_i32 m0, s57, 0x2000
	s_nop 0
	global_load_lds_dwordx4 v144, s[58:59]
	s_waitcnt vmcnt(6)
	s_waitcnt lgkmcnt(0)
	s_setprio 1
	s_barrier
	v_mfma_f32_16x16x32_bf16 v[62:65], v[130:133], v[204:207], v[62:65]
	v_mfma_f32_16x16x32_bf16 v[58:61], v[178:181], v[204:207], v[58:61]
	v_mfma_f32_16x16x32_bf16 v[46:49], v[130:133], v[212:215], v[46:49]
	v_mfma_f32_16x16x32_bf16 v[42:45], v[178:181], v[212:215], v[42:45]
	v_mfma_f32_16x16x32_bf16 v[30:33], v[130:133], v[220:223], v[30:33]
	v_mfma_f32_16x16x32_bf16 v[26:29], v[178:181], v[220:223], v[26:29]
	v_mfma_f32_16x16x32_bf16 v[14:17], v[130:133], v[228:231], v[14:17]
	v_mfma_f32_16x16x32_bf16 v[10:13], v[178:181], v[228:231], v[10:13]
	v_mfma_f32_16x16x32_bf16 v[62:65], v[134:137], v[208:211], v[62:65]
	v_mfma_f32_16x16x32_bf16 v[58:61], v[182:185], v[208:211], v[58:61]
	v_mfma_f32_16x16x32_bf16 v[46:49], v[134:137], v[216:219], v[46:49]
	v_mfma_f32_16x16x32_bf16 v[42:45], v[182:185], v[216:219], v[42:45]
	v_mfma_f32_16x16x32_bf16 v[30:33], v[134:137], v[224:227], v[30:33]
	v_mfma_f32_16x16x32_bf16 v[26:29], v[182:185], v[224:227], v[26:29]
	v_mfma_f32_16x16x32_bf16 v[14:17], v[134:137], v[232:235], v[14:17]
	v_mfma_f32_16x16x32_bf16 v[10:13], v[182:185], v[232:235], v[10:13]
	v_mfma_f32_16x16x32_bf16 v[54:57], v[186:189], v[204:207], v[54:57]
	v_mfma_f32_16x16x32_bf16 v[50:53], v[194:197], v[204:207], v[50:53]
	v_mfma_f32_16x16x32_bf16 v[38:41], v[186:189], v[212:215], v[38:41]
	v_mfma_f32_16x16x32_bf16 v[34:37], v[194:197], v[212:215], v[34:37]
	v_mfma_f32_16x16x32_bf16 v[22:25], v[186:189], v[220:223], v[22:25]
	v_mfma_f32_16x16x32_bf16 v[18:21], v[194:197], v[220:223], v[18:21]
	v_mfma_f32_16x16x32_bf16 v[6:9], v[186:189], v[228:231], v[6:9]
	v_mfma_f32_16x16x32_bf16 v[2:5], v[194:197], v[228:231], v[2:5]
	v_mfma_f32_16x16x32_bf16 v[54:57], v[190:193], v[208:211], v[54:57]
	v_mfma_f32_16x16x32_bf16 v[50:53], v[200:203], v[208:211], v[50:53]
	v_mfma_f32_16x16x32_bf16 v[38:41], v[190:193], v[216:219], v[38:41]
	v_mfma_f32_16x16x32_bf16 v[34:37], v[200:203], v[216:219], v[34:37]
	v_mfma_f32_16x16x32_bf16 v[22:25], v[190:193], v[224:227], v[22:25]
	v_mfma_f32_16x16x32_bf16 v[18:21], v[200:203], v[224:227], v[18:21]
	v_mfma_f32_16x16x32_bf16 v[6:9], v[190:193], v[232:235], v[6:9]
	v_mfma_f32_16x16x32_bf16 v[2:5], v[200:203], v[232:235], v[2:5]
	s_barrier
; #define PG8_STAGE(bufoff, gbase, voff) do { _Pragma("unroll") for (int _i = 0; _i < 2; ++_i) \
;         __builtin_amdgcn_global_load_lds((const unsigned*)((const char*)(gbase) + (voff)[_i]), (PG8_LAS unsigned*)(lds + (bufoff) + ldsw + _i * 8192), 16, 0, 0); } while (0)
; #define PG8_LDA(dst, b, h) do { _Pragma("unroll") for (int m = 0; m < 4; ++m) _Pragma("unroll") for (int k = 0; k < 2; ++k) dst[m][k] = *(const PG8_LAS bf16x8*)(lds + PG8_SA(b, h) + aoff + m * 2048 + k * 1024); } while (0)
; #define PG8_LDB(dst, b, h) do { _Pragma("unroll") for (int n = 0; n < 2; ++n) _Pragma("unroll") for (int k = 0; k < 2; ++k) dst[n][k] = *(const PG8_LAS bf16x8*)(lds + PG8_SB(b, h) + boff + n * 2048 + k * 1024); } while (0)
; #define PG8_MMA(ai, bj, At, Bt) do { __builtin_amdgcn_s_setprio(1); _Pragma("unroll") for (int m = 0; m < 4; ++m) _Pragma("unroll") for (int n = 0; n < 2; ++n) _Pragma("unroll") for (int k = 0; k < 2; ++k) \
;         acc[ai][bj][m][n] = __builtin_amdgcn_mfma_f32_16x16x32_bf16(Bt[n][k], At[m][k], acc[ai][bj][m][n], 0, 0, 0); __builtin_amdgcn_s_setprio(0); } while (0)
; #define PG8_WAIT_V(n) asm volatile("s_waitcnt vmcnt(" #n ")" ::: "memory")
; #define PG8_WAIT_L(n) asm volatile("s_waitcnt lgkmcnt(" #n ")" ::: "memory")
; #define PG8_BAR __builtin_amdgcn_s_barrier()
; #define PG8_SCHED __builtin_amdgcn_sched_barrier(0)
; template <class Epi, class Sched, bool ALIGN_EPI = false, bool SP2 = false>
; __device__ __forceinline__ void gemm_phase(PG8_LAS unsigned char* lds, const Gemm g, const Sched& S, const Epi& E) {
;     ...
;         for (int t = 0; t < nt; t += 2) {
;             const bool last = (t == nt - 2);
;             const char* a1 = cA + (size_t)(t + 1) * kstep;
;             const char* a2 = last ? nA : cA + (size_t)(t + 2) * kstep; const char* b2 = last ? nB : cB + (size_t)(t + 2) * kstep;
;     ...
;             PG8_LDB(B0, 1, 0); PG8_LDB(B1, 1, 1); PG8_SCHED; PG8_LDA(At, 1, 0); PG8_STAGE(PG8_SA(0, 1), a2 + hstep, voffA);
;             PG8_WAIT_V(8); PG8_WAIT_L(0); PG8_BAR; PG8_MMA(0, 0, At, B0); PG8_MMA(0, 1, At, B1); PG8_BAR; PG8_SCHED;
;             PG8_LDA(At, 1, 1); PG8_STAGE(PG8_SB(1, 0), b3, voffB); PG8_STAGE(PG8_SB(1, 1), b3 + hstep, voffB); PG8_STAGE(PG8_SA(1, 0), a3, voffA);
;             PG8_WAIT_V(8); PG8_WAIT_L(0); PG8_BAR; PG8_MMA(1, 0, At, B0); PG8_MMA(1, 1, At, B1); PG8_BAR; PG8_SCHED;
	s_setprio 0
	s_mov_b32 m0, s40
	s_nop 0
	global_load_lds_dwordx4 v138, s[38:39]
	s_mov_b32 m0, s41
	s_nop 0
	global_load_lds_dwordx4 v142, s[38:39]
	s_add_i32 s57, 0, 0x18000
	v_add_u32_e32 v146, s57, v159
	s_add_i32 s58, 0, 0x1c000
	ds_read_b128 v[130:133], v146
	ds_read_b128 v[134:137], v146 offset:1024
	ds_read_b128 v[178:181], v146 offset:2048
	ds_read_b128 v[182:185], v146 offset:3072
	v_add_u32_e32 v146, s58, v159
	ds_read_b128 v[186:189], v146
	ds_read_b128 v[190:193], v146 offset:1024
	ds_read_b128 v[194:197], v146 offset:2048
	ds_read_b128 v[200:203], v146 offset:3072
	s_add_u32 s38, s38, 0x100000
	s_addc_u32 s39, s39, 0
	s_mov_b32 m0, s42
	ds_read_b128 v[204:207], v172 offset:32768
	ds_read_b128 v[208:211], v172 offset:33792
	ds_read_b128 v[212:215], v172 offset:34816
	ds_read_b128 v[216:219], v172 offset:35840
	ds_read_b128 v[220:223], v172 offset:36864
	ds_read_b128 v[224:227], v172 offset:37888
	ds_read_b128 v[228:231], v172 offset:38912
	ds_read_b128 v[232:235], v172 offset:39936
	global_load_lds_dwordx4 v138, s[38:39]
	s_mov_b32 m0, s43
	s_nop 0
	global_load_lds_dwordx4 v142, s[38:39]
	s_waitcnt vmcnt(8)
	s_waitcnt lgkmcnt(0)
	s_setprio 1
	s_barrier
	v_mfma_f32_16x16x32_bf16 v[126:129], v[130:133], v[204:207], v[126:129]
	v_mfma_f32_16x16x32_bf16 v[122:125], v[178:181], v[204:207], v[122:125]
	v_mfma_f32_16x16x32_bf16 v[110:113], v[130:133], v[212:215], v[110:113]
	v_mfma_f32_16x16x32_bf16 v[106:109], v[178:181], v[212:215], v[106:109]
	v_mfma_f32_16x16x32_bf16 v[94:97], v[130:133], v[220:223], v[94:97]
	v_mfma_f32_16x16x32_bf16 v[90:93], v[178:181], v[220:223], v[90:93]
	v_mfma_f32_16x16x32_bf16 v[78:81], v[130:133], v[228:231], v[78:81]
	v_mfma_f32_16x16x32_bf16 v[74:77], v[178:181], v[228:231], v[74:77]
	v_mfma_f32_16x16x32_bf16 v[126:129], v[134:137], v[208:211], v[126:129]
	v_mfma_f32_16x16x32_bf16 v[122:125], v[182:185], v[208:211], v[122:125]
	v_mfma_f32_16x16x32_bf16 v[110:113], v[134:137], v[216:219], v[110:113]
	v_mfma_f32_16x16x32_bf16 v[106:109], v[182:185], v[216:219], v[106:109]
	v_mfma_f32_16x16x32_bf16 v[94:97], v[134:137], v[224:227], v[94:97]
	v_mfma_f32_16x16x32_bf16 v[90:93], v[182:185], v[224:227], v[90:93]
	v_mfma_f32_16x16x32_bf16 v[78:81], v[134:137], v[232:235], v[78:81]
	v_mfma_f32_16x16x32_bf16 v[74:77], v[182:185], v[232:235], v[74:77]
	v_mfma_f32_16x16x32_bf16 v[118:121], v[186:189], v[204:207], v[118:121]
	v_mfma_f32_16x16x32_bf16 v[114:117], v[194:197], v[204:207], v[114:117]
	v_mfma_f32_16x16x32_bf16 v[102:105], v[186:189], v[212:215], v[102:105]
	v_mfma_f32_16x16x32_bf16 v[98:101], v[194:197], v[212:215], v[98:101]
	v_mfma_f32_16x16x32_bf16 v[86:89], v[186:189], v[220:223], v[86:89]
	v_mfma_f32_16x16x32_bf16 v[82:85], v[194:197], v[220:223], v[82:85]
	v_mfma_f32_16x16x32_bf16 v[70:73], v[186:189], v[228:231], v[70:73]
	v_mfma_f32_16x16x32_bf16 v[66:69], v[194:197], v[228:231], v[66:69]
	v_mfma_f32_16x16x32_bf16 v[118:121], v[190:193], v[208:211], v[118:121]
	v_mfma_f32_16x16x32_bf16 v[114:117], v[200:203], v[208:211], v[114:117]
	v_mfma_f32_16x16x32_bf16 v[102:105], v[190:193], v[216:219], v[102:105]
	v_mfma_f32_16x16x32_bf16 v[98:101], v[200:203], v[216:219], v[98:101]
	v_mfma_f32_16x16x32_bf16 v[86:89], v[190:193], v[224:227], v[86:89]
	v_mfma_f32_16x16x32_bf16 v[82:85], v[200:203], v[224:227], v[82:85]
	v_mfma_f32_16x16x32_bf16 v[70:73], v[190:193], v[232:235], v[70:73]
	v_mfma_f32_16x16x32_bf16 v[66:69], v[200:203], v[232:235], v[66:69]
	s_barrier
	s_setprio 0
	s_add_i32 s38, s57, s33
	s_add_u32 s36, s36, 0x80
	s_addc_u32 s37, s37, 0
	s_mov_b32 m0, s38
	ds_read_b128 v[204:207], v172 offset:49152
	ds_read_b128 v[208:211], v172 offset:50176
	ds_read_b128 v[212:215], v172 offset:51200
	ds_read_b128 v[216:219], v172 offset:52224
	ds_read_b128 v[220:223], v172 offset:53248
	ds_read_b128 v[224:227], v172 offset:54272
	ds_read_b128 v[228:231], v172 offset:55296
	ds_read_b128 v[232:235], v172 offset:56320
	global_load_lds_dwordx4 v140, s[36:37]
	s_add_i32 m0, s38, 0x2000
	s_add_i32 s38, s58, s33
	global_load_lds_dwordx4 v144, s[36:37]
	s_add_u32 s36, s36, 0x100000
	s_addc_u32 s37, s37, 0
	s_mov_b32 m0, s38
	s_nop 0
	global_load_lds_dwordx4 v140, s[36:37]
	s_add_i32 m0, s38, 0x2000
	s_nop 0
	global_load_lds_dwordx4 v144, s[36:37]
	s_waitcnt vmcnt(6)
	s_waitcnt lgkmcnt(0)
	s_setprio 1
	s_barrier
	v_mfma_f32_16x16x32_bf16 v[62:65], v[130:133], v[204:207], v[62:65]
	v_mfma_f32_16x16x32_bf16 v[58:61], v[178:181], v[204:207], v[58:61]
	v_mfma_f32_16x16x32_bf16 v[46:49], v[130:133], v[212:215], v[46:49]
	v_mfma_f32_16x16x32_bf16 v[42:45], v[178:181], v[212:215], v[42:45]
	v_mfma_f32_16x16x32_bf16 v[30:33], v[130:133], v[220:223], v[30:33]
	v_mfma_f32_16x16x32_bf16 v[26:29], v[178:181], v[220:223], v[26:29]
	v_mfma_f32_16x16x32_bf16 v[14:17], v[130:133], v[228:231], v[14:17]
	v_mfma_f32_16x16x32_bf16 v[10:13], v[178:181], v[228:231], v[10:13]
	v_mfma_f32_16x16x32_bf16 v[62:65], v[134:137], v[208:211], v[62:65]
	v_mfma_f32_16x16x32_bf16 v[58:61], v[182:185], v[208:211], v[58:61]
	v_mfma_f32_16x16x32_bf16 v[46:49], v[134:137], v[216:219], v[46:49]
	v_mfma_f32_16x16x32_bf16 v[42:45], v[182:185], v[216:219], v[42:45]
	v_mfma_f32_16x16x32_bf16 v[30:33], v[134:137], v[224:227], v[30:33]
	v_mfma_f32_16x16x32_bf16 v[26:29], v[182:185], v[224:227], v[26:29]
	v_mfma_f32_16x16x32_bf16 v[14:17], v[134:137], v[232:235], v[14:17]
	v_mfma_f32_16x16x32_bf16 v[10:13], v[182:185], v[232:235], v[10:13]
	v_mfma_f32_16x16x32_bf16 v[54:57], v[186:189], v[204:207], v[54:57]
	v_mfma_f32_16x16x32_bf16 v[50:53], v[194:197], v[204:207], v[50:53]
	v_mfma_f32_16x16x32_bf16 v[38:41], v[186:189], v[212:215], v[38:41]
	v_mfma_f32_16x16x32_bf16 v[34:37], v[194:197], v[212:215], v[34:37]
	v_mfma_f32_16x16x32_bf16 v[22:25], v[186:189], v[220:223], v[22:25]
	v_mfma_f32_16x16x32_bf16 v[18:21], v[194:197], v[220:223], v[18:21]
	v_mfma_f32_16x16x32_bf16 v[6:9], v[186:189], v[228:231], v[6:9]
	v_mfma_f32_16x16x32_bf16 v[2:5], v[194:197], v[228:231], v[2:5]
	v_mfma_f32_16x16x32_bf16 v[54:57], v[190:193], v[208:211], v[54:57]
	v_mfma_f32_16x16x32_bf16 v[50:53], v[200:203], v[208:211], v[50:53]
	v_mfma_f32_16x16x32_bf16 v[38:41], v[190:193], v[216:219], v[38:41]
	v_mfma_f32_16x16x32_bf16 v[34:37], v[200:203], v[216:219], v[34:37]
	v_mfma_f32_16x16x32_bf16 v[22:25], v[190:193], v[224:227], v[22:25]
	v_mfma_f32_16x16x32_bf16 v[18:21], v[200:203], v[224:227], v[18:21]
	v_mfma_f32_16x16x32_bf16 v[6:9], v[190:193], v[232:235], v[6:9]
	v_mfma_f32_16x16x32_bf16 v[2:5], v[200:203], v[232:235], v[2:5]
	s_barrier
	s_setprio 0
	s_add_i32 s56, s56, 2
	s_add_u32 s34, s34, 0x100
	s_addc_u32 s35, s35, 0
	s_add_u32 s54, s54, 0x100
	s_addc_u32 s55, s55, 0
	s_cmp_gt_u32 s56, 61
	s_cbranch_scc0 .LBB0_180
	s_and_b64 vcc, exec, s[12:13]
	s_cbranch_vccz .LBB0_183
	s_barrier

; __device__ __forceinline__ unsigned cvt_pk_bf16(float lo, float hi) { unsigned r; asm volatile("v_cvt_pk_bf16_f32 %0, %1, %2" : "=v"(r) : "v"(lo), "v"(hi)); return r; }
;     __device__ __forceinline__ void operator()(const f32x4 (&acc)[2][2][4][2], const Unit& u, int wr, int wc, int fr, int fq) const {
;     ...
; #pragma unroll
;         for (int ai = 0; ai < 2; ++ai)
; #pragma unroll
;             for (int m = 0; m < 4; ++m) { bf16_t* rowp = O + (size_t)(row0 + ai * HALF + m * 16) * ldc + col0;
; #pragma unroll
;                 for (int bj = 0; bj < 2; ++bj) { const f32x4 v0 = acc[ai][bj][m][0], v1 = acc[ai][bj][m][1];
;                     u32x4 w; w.x = cvt_pk_bf16(v0[0], v0[1]); w.y = cvt_pk_bf16(v0[2], v0[3]); w.z = cvt_pk_bf16(v1[0], v1[1]); w.w = cvt_pk_bf16(v1[2], v1[3]);
;                     *(u32x4*)(rowp + bj * HALF) = w; } }
.Lbp_epi:
	s_mov_b32 s32, 1
	v_mbcnt_lo_u32_b32 v236, -1, 0
	v_mbcnt_hi_u32_b32 v236, -1, v236
	v_and_b32_e32 v237, 3, v236
	v_lshrrev_b32_e32 v236, 2, v236
	v_lshl_add_u32 v252, v237, 4, v236
	v_lshlrev_b32_e32 v252, 2, v252
	v_and_b32_e32 v253, 64, v158
	v_add_u32_e32 v253, v253, v236
	v_mul_u32_u24_e32 v253, 0xb000, v253
	v_lshrrev_b32_e32 v236, 5, v169
	v_lshl_add_u32 v253, v236, 6, v253
	v_lshl_add_u32 v253, v237, 4, v253
	v_cvt_pk_bf16_f32 v126, v126, v127
	v_cvt_pk_bf16_f32 v127, v128, v129
	v_cvt_pk_bf16_f32 v128, v122, v123
	v_cvt_pk_bf16_f32 v129, v124, v125
	v_cvt_pk_bf16_f32 v118, v118, v119
	v_cvt_pk_bf16_f32 v119, v120, v121
	v_cvt_pk_bf16_f32 v120, v114, v115
	v_cvt_pk_bf16_f32 v121, v116, v117
	ds_bpermute_b32 v236, v252, v126
	ds_bpermute_b32 v237, v252, v127
	ds_bpermute_b32 v238, v252, v128
	ds_bpermute_b32 v239, v252, v129
	ds_bpermute_b32 v240, v252, v118
	ds_bpermute_b32 v241, v252, v119
	ds_bpermute_b32 v242, v252, v120
	ds_bpermute_b32 v243, v252, v121
	v_cvt_pk_bf16_f32 v110, v110, v111
	v_cvt_pk_bf16_f32 v111, v112, v113
	v_cvt_pk_bf16_f32 v112, v106, v107
	v_cvt_pk_bf16_f32 v113, v108, v109
	v_cvt_pk_bf16_f32 v102, v102, v103
	v_cvt_pk_bf16_f32 v103, v104, v105
	v_cvt_pk_bf16_f32 v104, v98, v99
	v_cvt_pk_bf16_f32 v105, v100, v101
	ds_bpermute_b32 v244, v252, v110
	ds_bpermute_b32 v245, v252, v111
	ds_bpermute_b32 v246, v252, v112
	ds_bpermute_b32 v247, v252, v113
	ds_bpermute_b32 v248, v252, v102
	ds_bpermute_b32 v249, v252, v103
	ds_bpermute_b32 v250, v252, v104
	ds_bpermute_b32 v251, v252, v105
	s_waitcnt lgkmcnt(8)
	s_mov_b64 s[22:23], s[20:21]
	global_store_dwordx4 v253, v[236:239], s[22:23]
	global_store_dwordx4 v253, v[240:243], s[22:23] offset:256
	v_cvt_pk_bf16_f32 v94, v94, v95
	v_cvt_pk_bf16_f32 v95, v96, v97
	v_cvt_pk_bf16_f32 v96, v90, v91
	v_cvt_pk_bf16_f32 v97, v92, v93
	v_cvt_pk_bf16_f32 v86, v86, v87
	v_cvt_pk_bf16_f32 v87, v88, v89
	v_cvt_pk_bf16_f32 v88, v82, v83
	v_cvt_pk_bf16_f32 v89, v84, v85
	ds_bpermute_b32 v236, v252, v94
	ds_bpermute_b32 v237, v252, v95
	ds_bpermute_b32 v238, v252, v96
	ds_bpermute_b32 v239, v252, v97
	ds_bpermute_b32 v240, v252, v86
	ds_bpermute_b32 v241, v252, v87
	ds_bpermute_b32 v242, v252, v88
	ds_bpermute_b32 v243, v252, v89
	s_waitcnt lgkmcnt(8)
	s_add_u32 s22, s20, 0xb0000
	s_addc_u32 s23, s21, 0
	global_store_dwordx4 v253, v[244:247], s[22:23]
	global_store_dwordx4 v253, v[248:251], s[22:23] offset:256
	v_cvt_pk_bf16_f32 v78, v78, v79
	v_cvt_pk_bf16_f32 v79, v80, v81
	v_cvt_pk_bf16_f32 v80, v74, v75
	v_cvt_pk_bf16_f32 v81, v76, v77
	v_cvt_pk_bf16_f32 v70, v70, v71
	v_cvt_pk_bf16_f32 v71, v72, v73
	v_cvt_pk_bf16_f32 v72, v66, v67
	v_cvt_pk_bf16_f32 v73, v68, v69
	ds_bpermute_b32 v244, v252, v78
	ds_bpermute_b32 v245, v252, v79
	ds_bpermute_b32 v246, v252, v80
	ds_bpermute_b32 v247, v252, v81
	ds_bpermute_b32 v248, v252, v70
	ds_bpermute_b32 v249, v252, v71
	ds_bpermute_b32 v250, v252, v72
	ds_bpermute_b32 v251, v252, v73
	s_waitcnt lgkmcnt(8)
	s_add_u32 s22, s20, 0x160000
	s_addc_u32 s23, s21, 0
	global_store_dwordx4 v253, v[236:239], s[22:23]
	global_store_dwordx4 v253, v[240:243], s[22:23] offset:256
	v_cvt_pk_bf16_f32 v62, v62, v63
	v_cvt_pk_bf16_f32 v63, v64, v65
	v_cvt_pk_bf16_f32 v64, v58, v59
	v_cvt_pk_bf16_f32 v65, v60, v61
	v_cvt_pk_bf16_f32 v54, v54, v55
	v_cvt_pk_bf16_f32 v55, v56, v57
	v_cvt_pk_bf16_f32 v56, v50, v51
	v_cvt_pk_bf16_f32 v57, v52, v53
	ds_bpermute_b32 v236, v252, v62
	ds_bpermute_b32 v237, v252, v63
	ds_bpermute_b32 v238, v252, v64
	ds_bpermute_b32 v239, v252, v65
	ds_bpermute_b32 v240, v252, v54
	ds_bpermute_b32 v241, v252, v55
	ds_bpermute_b32 v242, v252, v56
	ds_bpermute_b32 v243, v252, v57
	s_waitcnt lgkmcnt(8)
	s_add_u32 s22, s20, 0x210000
	s_addc_u32 s23, s21, 0
	global_store_dwordx4 v253, v[244:247], s[22:23]
	global_store_dwordx4 v253, v[248:251], s[22:23] offset:256
	v_cvt_pk_bf16_f32 v46, v46, v47
	v_cvt_pk_bf16_f32 v47, v48, v49
	v_cvt_pk_bf16_f32 v48, v42, v43
	v_cvt_pk_bf16_f32 v49, v44, v45
	v_cvt_pk_bf16_f32 v38, v38, v39
	v_cvt_pk_bf16_f32 v39, v40, v41
	v_cvt_pk_bf16_f32 v40, v34, v35
	v_cvt_pk_bf16_f32 v41, v36, v37
	ds_bpermute_b32 v244, v252, v46
	ds_bpermute_b32 v245, v252, v47
	ds_bpermute_b32 v246, v252, v48
	ds_bpermute_b32 v247, v252, v49
	ds_bpermute_b32 v248, v252, v38
	ds_bpermute_b32 v249, v252, v39
	ds_bpermute_b32 v250, v252, v40
	ds_bpermute_b32 v251, v252, v41
	s_waitcnt lgkmcnt(8)
	s_add_u32 s22, s20, 0x580000
	s_addc_u32 s23, s21, 0
	global_store_dwordx4 v253, v[236:239], s[22:23]
	global_store_dwordx4 v253, v[240:243], s[22:23] offset:256
	v_cvt_pk_bf16_f32 v30, v30, v31
	v_cvt_pk_bf16_f32 v31, v32, v33
	v_cvt_pk_bf16_f32 v32, v26, v27
	v_cvt_pk_bf16_f32 v33, v28, v29
	v_cvt_pk_bf16_f32 v22, v22, v23
	v_cvt_pk_bf16_f32 v23, v24, v25
	v_cvt_pk_bf16_f32 v24, v18, v19
	v_cvt_pk_bf16_f32 v25, v20, v21
	ds_bpermute_b32 v236, v252, v30
	ds_bpermute_b32 v237, v252, v31
	ds_bpermute_b32 v238, v252, v32
	ds_bpermute_b32 v239, v252, v33
	ds_bpermute_b32 v240, v252, v22
	ds_bpermute_b32 v241, v252, v23
	ds_bpermute_b32 v242, v252, v24
	ds_bpermute_b32 v243, v252, v25
	s_waitcnt lgkmcnt(8)
	s_add_u32 s22, s20, 0x630000
	s_addc_u32 s23, s21, 0
	global_store_dwordx4 v253, v[244:247], s[22:23]
	global_store_dwordx4 v253, v[248:251], s[22:23] offset:256
	v_cvt_pk_bf16_f32 v14, v14, v15
	v_cvt_pk_bf16_f32 v15, v16, v17
	v_cvt_pk_bf16_f32 v16, v10, v11
	v_cvt_pk_bf16_f32 v17, v12, v13
	v_cvt_pk_bf16_f32 v6, v6, v7
	v_cvt_pk_bf16_f32 v7, v8, v9
	v_cvt_pk_bf16_f32 v8, v2, v3
	v_cvt_pk_bf16_f32 v9, v4, v5
	ds_bpermute_b32 v244, v252, v14
	ds_bpermute_b32 v245, v252, v15
	ds_bpermute_b32 v246, v252, v16
	ds_bpermute_b32 v247, v252, v17
	ds_bpermute_b32 v248, v252, v6
	ds_bpermute_b32 v249, v252, v7
	ds_bpermute_b32 v250, v252, v8
	ds_bpermute_b32 v251, v252, v9
	s_waitcnt lgkmcnt(8)
	s_add_u32 s22, s20, 0x6e0000
	s_addc_u32 s23, s21, 0
	global_store_dwordx4 v253, v[236:239], s[22:23]
	global_store_dwordx4 v253, v[240:243], s[22:23] offset:256
	s_waitcnt lgkmcnt(0)
	s_add_u32 s22, s20, 0x790000
	s_addc_u32 s23, s21, 0
	global_store_dwordx4 v253, v[244:247], s[22:23]
	global_store_dwordx4 v253, v[248:251], s[22:23] offset:256
	s_andn2_b64 vcc, exec, s[4:5]
	s_mov_b64 s[4:5], -1
	s_cbranch_vccnz .LBB0_176
	s_branch .LBB0_220

;     __device__ __forceinline__ void operator()(const f32x4 (&acc)[2][2][4][2], const Unit& u, int wr, int wc, int fr, int fq) const {
;     ...
;         if (u.pn >= qn_lo && u.pn < qn_hi) {
;             const float* wp = (u.pn < qn_mid ? wq : wk) + wc * 32 + 8 * fq;
;             const f32x4 w0 = *(const f32x4*)wp, w1 = *(const f32x4*)(wp + 4);
; #pragma unroll
;             for (int ai = 0; ai < 2; ++ai)
; #pragma unroll
;                 for (int m = 0; m < 4; ++m)
; #pragma unroll
;                     for (int bj = 0; bj < 2; ++bj) { const f32x4 v0 = acc[ai][bj][m][0], v1 = acc[ai][bj][m][1];
;                         float ss = v0[0] * v0[0] + v0[1] * v0[1] + v0[2] * v0[2] + v0[3] * v0[3] + v1[0] * v1[0] + v1[1] * v1[1] + v1[2] * v1[2] + v1[3] * v1[3];
;                         ss += __shfl_xor(ss, 16); ss += __shfl_xor(ss, 32);
;                         if (fq == 0) part[(ai * HALF + wr * 64 + m * 16 + fr) * 8 + bj * 4 + wc] = ss; }
.LBB0_187:
	s_mov_b32 s32, 0
	s_cmp_lt_u32 s6, 40
	s_cselect_b32 s6, s80, s82
	s_cselect_b32 s7, s81, s83
	s_add_u32 s6, s6, s52
	s_addc_u32 s7, s7, 0
	global_load_dwordx4 v[130:133], v173, s[6:7] offset:16
	global_load_dwordx4 v[134:137], v173, s[6:7]
	v_mul_f32_e32 v185, v127, v127
	v_fmac_f32_e32 v185, v126, v126
	v_fmac_f32_e32 v185, v128, v128
	v_and_b32_e32 v157, 64, v176
	v_fmac_f32_e32 v185, v129, v129
	v_xor_b32_e32 v156, 16, v176
	v_add_u32_e32 v157, 64, v157
	v_fmac_f32_e32 v185, v122, v122
	v_cmp_lt_i32_e32 vcc, v156, v157
	v_fmac_f32_e32 v185, v123, v123
	v_fmac_f32_e32 v185, v124, v124
	v_cndmask_b32_e32 v156, v176, v156, vcc
	v_lshlrev_b32_e32 v156, 2, v156
	v_fmac_f32_e32 v185, v125, v125
	ds_bpermute_b32 v186, v156, v185
	v_xor_b32_e32 v187, 32, v176
	v_cmp_lt_i32_e32 vcc, v187, v157
	s_waitcnt lgkmcnt(0)
	v_add_f32_e32 v185, v185, v186
	v_cndmask_b32_e32 v157, v176, v187, vcc
	v_lshlrev_b32_e32 v157, 2, v157
	ds_bpermute_b32 v186, v157, v185
	s_and_saveexec_b64 s[6:7], s[0:1]
	s_cbranch_execz .LBB0_189
	s_waitcnt lgkmcnt(0)
	v_add_f32_e32 v185, v185, v186
	ds_write_b32 v161, v185

; __device__ __forceinline__ unsigned cvt_pk_bf16(float lo, float hi) { unsigned r; asm volatile("v_cvt_pk_bf16_f32 %0, %1, %2" : "=v"(r) : "v"(lo), "v"(hi)); return r; }
; __device__ __forceinline__ float sigmoid_f(float x) { return __builtin_amdgcn_rcpf(1.0f + __builtin_amdgcn_exp2f(-1.4426950408889634f * x)); }
;     __device__ __forceinline__ void operator()(const f32x4 (&acc)[2][2][4][2], const Unit& u, int wr, int wc, int fr, int fq) const {
;         const int row0 = u.pm * BM + wr * 64 + fr, col0 = u.pn * HALF + wc * 32 + 8 * fq;
; #pragma unroll
;         for (int ai = 0; ai < 2; ++ai)
; #pragma unroll
;             for (int m = 0; m < 4; ++m) { bf16_t* rowp = ACT + (size_t)(row0 + ai * HALF + m * 16) * ldc + col0;
;                 float v[8];
; #pragma unroll
;                 for (int n = 0; n < 2; ++n)
; #pragma unroll
;                     for (int j = 0; j < 4; ++j) { const float g = acc[ai][0][m][n][j], up = acc[ai][1][m][n][j]; v[4 * n + j] = g * sigmoid_f(g) * up; }
;                 u32x4 w; w.x = cvt_pk_bf16(v[0], v[1]); w.y = cvt_pk_bf16(v[2], v[3]); w.z = cvt_pk_bf16(v[4], v[5]); w.w = cvt_pk_bf16(v[6], v[7]);
;                 *(u32x4*)rowp = w; }
.LBB0_1084:
	s_mul_i32 s74, s28, 0x560000
	s_lshl_b32 s75, s50, 8
	s_add_u32 s74, s74, s75
	s_addc_u32 s75, 0, 0
	s_add_u32 s74, s74, s2
	s_addc_u32 s75, s75, s3
	v_mbcnt_lo_u32_b32 v250, -1, 0
	v_mbcnt_hi_u32_b32 v250, -1, v250
	v_and_b32_e32 v251, 3, v250
	v_lshrrev_b32_e32 v250, 2, v250
	v_lshl_add_u32 v252, v251, 4, v250
	v_lshlrev_b32_e32 v252, 2, v252
	v_and_b32_e32 v253, 64, v1
	v_add_u32_e32 v253, v253, v250
	v_mul_u32_u24_e32 v253, 0x5600, v253
	v_lshrrev_b32_e32 v250, 5, v149
	v_lshl_add_u32 v253, v250, 6, v253
	v_lshl_add_u32 v253, v251, 4, v253
	v_mul_f32_e32 v146, 0xbfb8aa3b, v126
	v_exp_f32_e32 v156, v146
	v_mul_f32_e32 v146, 0xbfb8aa3b, v127
	v_exp_f32_e32 v157, v146
	v_lshl_or_b32 v154, s50, 7, v149
	v_add_f32_e32 v156, 1.0, v156
	v_rcp_f32_e32 v158, v156
	v_add_f32_e32 v156, 1.0, v157
	v_rcp_f32_e32 v159, v156
	v_lshl_add_u32 v153, s28, 8, v1
	v_mul_f32_e32 v126, v126, v158
	v_mul_f32_e32 v118, v126, v118
	v_mul_f32_e32 v126, v127, v159
	v_mul_f32_e32 v127, 0xbfb8aa3b, v128
	v_exp_f32_e32 v127, v127
	v_mul_f32_e32 v158, 0xbfb8aa3b, v129
	v_exp_f32_e32 v158, v158
	v_mul_f32_e32 v119, v126, v119
	v_add_f32_e32 v126, 1.0, v127
	v_rcp_f32_e32 v126, v126
	v_add_f32_e32 v127, 1.0, v158
	v_mul_f32_e32 v158, 0xbfb8aa3b, v122
	v_rcp_f32_e32 v127, v127
	v_exp_f32_e32 v158, v158
	v_mul_f32_e32 v126, v128, v126
	v_mul_f32_e32 v126, v126, v120
	v_mul_f32_e32 v120, v129, v127
	v_add_f32_e32 v127, 1.0, v158
	v_rcp_f32_e32 v127, v127
	v_mul_f32_e32 v128, 0xbfb8aa3b, v123
	v_mul_f32_e32 v129, v120, v121
	v_exp_f32_e32 v128, v128
	v_mul_f32_e32 v120, v122, v127
	v_mul_f32_e32 v122, v120, v114
	v_mul_f32_e32 v120, 0xbfb8aa3b, v124
	v_exp_f32_e32 v120, v120
	v_mul_f32_e32 v121, 0xbfb8aa3b, v125
	v_exp_f32_e32 v121, v121
	v_add_f32_e32 v114, 1.0, v128
	v_rcp_f32_e32 v114, v114
	v_add_f32_e32 v120, 1.0, v120
	v_rcp_f32_e32 v120, v120
	v_add_f32_e32 v121, 1.0, v121
	v_rcp_f32_e32 v121, v121
	v_mul_f32_e32 v114, v123, v114
	v_mul_f32_e32 v123, v114, v115
	v_mul_f32_e32 v114, v124, v120
	v_ashrrev_i32_e32 v155, 31, v154
	v_mov_b64_e32 v[146:147], s[2:3]
	v_mul_f32_e32 v124, v114, v116
	v_mul_f32_e32 v114, v125, v121
	v_mad_i64_i32 v[156:157], s[30:31], v153, s49, v[146:147]
	v_mul_f32_e32 v125, v114, v117
	v_lshlrev_b64 v[114:115], 1, v[154:155]
	v_lshl_add_u64 v[120:121], v[156:157], 0, v[114:115]
	v_cvt_pk_bf16_f32 v116, v118, v119
	v_cvt_pk_bf16_f32 v117, v126, v129
	v_cvt_pk_bf16_f32 v118, v122, v123
	v_cvt_pk_bf16_f32 v119, v124, v125
	ds_bpermute_b32 v240, v252, v116
	ds_bpermute_b32 v241, v252, v117
	ds_bpermute_b32 v242, v252, v118
	ds_bpermute_b32 v243, v252, v119
	s_andn2_b64 vcc, exec, s[0:1]
	s_mov_b64 s[0:1], -1
	v_mul_f32_e32 v116, 0xbfb8aa3b, v110
	v_exp_f32_e32 v116, v116
	v_mul_f32_e32 v117, 0xbfb8aa3b, v111
	v_exp_f32_e32 v117, v117
	v_or_b32_e32 v118, 16, v153
	v_add_f32_e32 v116, 1.0, v116
	v_rcp_f32_e32 v119, v116
	v_add_f32_e32 v116, 1.0, v117
	v_rcp_f32_e32 v120, v116
	v_mad_i64_i32 v[116:117], s[30:31], v118, s49, v[146:147]
	v_mul_f32_e32 v110, v110, v119
	v_mul_f32_e32 v110, v110, v102
	v_mul_f32_e32 v102, v111, v120
	v_mul_f32_e32 v111, 0xbfb8aa3b, v112
	v_exp_f32_e32 v111, v111
	v_mul_f32_e32 v118, 0xbfb8aa3b, v113
	v_exp_f32_e32 v118, v118
	v_mul_f32_e32 v119, v102, v103
	v_add_f32_e32 v102, 1.0, v111
	v_rcp_f32_e32 v102, v102
	v_add_f32_e32 v103, 1.0, v118
	v_mul_f32_e32 v111, 0xbfb8aa3b, v106
	v_rcp_f32_e32 v103, v103
	v_exp_f32_e32 v111, v111
	v_mul_f32_e32 v102, v112, v102
	v_mul_f32_e32 v104, v102, v104
	v_mul_f32_e32 v102, v113, v103
	v_add_f32_e32 v103, 1.0, v111
	v_rcp_f32_e32 v103, v103
	v_mul_f32_e32 v111, 0xbfb8aa3b, v107
	v_mul_f32_e32 v105, v102, v105
	v_exp_f32_e32 v111, v111
	v_mul_f32_e32 v102, v106, v103
	v_mul_f32_e32 v106, v102, v98
	v_mul_f32_e32 v102, 0xbfb8aa3b, v108
	v_exp_f32_e32 v102, v102
	v_mul_f32_e32 v103, 0xbfb8aa3b, v109
	v_exp_f32_e32 v103, v103
	v_add_f32_e32 v98, 1.0, v111
	v_rcp_f32_e32 v98, v98
	v_add_f32_e32 v102, 1.0, v102
	v_rcp_f32_e32 v102, v102
	v_add_f32_e32 v103, 1.0, v103
	v_rcp_f32_e32 v103, v103
	v_mul_f32_e32 v98, v107, v98
	v_mul_f32_e32 v107, v98, v99
	v_mul_f32_e32 v98, v108, v102
	v_mul_f32_e32 v108, v98, v100
	v_mul_f32_e32 v98, v109, v103
	v_mul_f32_e32 v101, v98, v101
	v_lshl_add_u64 v[102:103], v[116:117], 0, v[114:115]
	v_cvt_pk_bf16_f32 v98, v110, v119
	v_cvt_pk_bf16_f32 v99, v104, v105
	v_cvt_pk_bf16_f32 v100, v106, v107
	v_cvt_pk_bf16_f32 v101, v108, v101
	ds_bpermute_b32 v244, v252, v98
	ds_bpermute_b32 v245, v252, v99
	ds_bpermute_b32 v246, v252, v100
	ds_bpermute_b32 v247, v252, v101
	s_waitcnt lgkmcnt(4)
	s_mov_b64 s[76:77], s[74:75]
	global_store_dwordx4 v253, v[240:243], s[76:77]
	s_nop 1
	v_mul_f32_e32 v98, 0xbfb8aa3b, v94
	v_exp_f32_e32 v98, v98
	v_mul_f32_e32 v99, 0xbfb8aa3b, v95
	v_exp_f32_e32 v99, v99
	v_or_b32_e32 v100, 32, v153
	v_add_f32_e32 v98, 1.0, v98
	v_rcp_f32_e32 v101, v98
	v_add_f32_e32 v98, 1.0, v99
	v_rcp_f32_e32 v102, v98
	v_mad_i64_i32 v[98:99], s[30:31], v100, s49, v[146:147]
	v_mul_f32_e32 v94, v94, v101
	v_mul_f32_e32 v94, v94, v86
	v_mul_f32_e32 v86, v95, v102
	v_mul_f32_e32 v95, 0xbfb8aa3b, v96
	v_exp_f32_e32 v95, v95
	v_mul_f32_e32 v100, 0xbfb8aa3b, v97
	v_exp_f32_e32 v100, v100
	v_mul_f32_e32 v101, v86, v87
	v_add_f32_e32 v86, 1.0, v95
	v_rcp_f32_e32 v86, v86
	v_add_f32_e32 v87, 1.0, v100
	v_mul_f32_e32 v95, 0xbfb8aa3b, v90
	v_rcp_f32_e32 v87, v87
	v_exp_f32_e32 v95, v95
	v_mul_f32_e32 v86, v96, v86
	v_mul_f32_e32 v88, v86, v88
	v_mul_f32_e32 v86, v97, v87
	v_add_f32_e32 v87, 1.0, v95
	v_rcp_f32_e32 v87, v87
	v_mul_f32_e32 v95, 0xbfb8aa3b, v91
	v_mul_f32_e32 v89, v86, v89
	v_exp_f32_e32 v95, v95
	v_mul_f32_e32 v86, v90, v87
	v_mul_f32_e32 v90, v86, v82
	v_mul_f32_e32 v86, 0xbfb8aa3b, v92
	v_exp_f32_e32 v86, v86
	v_mul_f32_e32 v87, 0xbfb8aa3b, v93
	v_exp_f32_e32 v87, v87
	v_add_f32_e32 v82, 1.0, v95
	v_rcp_f32_e32 v82, v82
	v_add_f32_e32 v86, 1.0, v86
	v_rcp_f32_e32 v86, v86
	v_add_f32_e32 v87, 1.0, v87
	v_rcp_f32_e32 v87, v87
	v_mul_f32_e32 v82, v91, v82
	v_mul_f32_e32 v91, v82, v83
	v_mul_f32_e32 v82, v92, v86
	v_mul_f32_e32 v92, v82, v84
	v_mul_f32_e32 v82, v93, v87
	v_mul_f32_e32 v85, v82, v85
	v_lshl_add_u64 v[86:87], v[98:99], 0, v[114:115]
	v_cvt_pk_bf16_f32 v82, v94, v101
	v_cvt_pk_bf16_f32 v83, v88, v89
	v_cvt_pk_bf16_f32 v84, v90, v91
	v_cvt_pk_bf16_f32 v85, v92, v85
	ds_bpermute_b32 v240, v252, v82
	ds_bpermute_b32 v241, v252, v83
	ds_bpermute_b32 v242, v252, v84
	ds_bpermute_b32 v243, v252, v85
	s_waitcnt lgkmcnt(4)
; __device__ __forceinline__ unsigned cvt_pk_bf16(float lo, float hi) { unsigned r; asm volatile("v_cvt_pk_bf16_f32 %0, %1, %2" : "=v"(r) : "v"(lo), "v"(hi)); return r; }
; __device__ __forceinline__ float sigmoid_f(float x) { return __builtin_amdgcn_rcpf(1.0f + __builtin_amdgcn_exp2f(-1.4426950408889634f * x)); }
;     __device__ __forceinline__ void operator()(const f32x4 (&acc)[2][2][4][2], const Unit& u, int wr, int wc, int fr, int fq) const {
;         const int row0 = u.pm * BM + wr * 64 + fr, col0 = u.pn * HALF + wc * 32 + 8 * fq;
; #pragma unroll
;         for (int ai = 0; ai < 2; ++ai)
; #pragma unroll
;             for (int m = 0; m < 4; ++m) { bf16_t* rowp = ACT + (size_t)(row0 + ai * HALF + m * 16) * ldc + col0;
;                 float v[8];
; #pragma unroll
;                 for (int n = 0; n < 2; ++n)
; #pragma unroll
;                     for (int j = 0; j < 4; ++j) { const float g = acc[ai][0][m][n][j], up = acc[ai][1][m][n][j]; v[4 * n + j] = g * sigmoid_f(g) * up; }
;                 u32x4 w; w.x = cvt_pk_bf16(v[0], v[1]); w.y = cvt_pk_bf16(v[2], v[3]); w.z = cvt_pk_bf16(v[4], v[5]); w.w = cvt_pk_bf16(v[6], v[7]);
;                 *(u32x4*)rowp = w; }
	s_add_u32 s76, s74, 0x56000
	s_addc_u32 s77, s75, 0
	global_store_dwordx4 v253, v[244:247], s[76:77]
	s_nop 1
	v_mul_f32_e32 v82, 0xbfb8aa3b, v78
	v_exp_f32_e32 v82, v82
	v_mul_f32_e32 v83, 0xbfb8aa3b, v79
	v_exp_f32_e32 v83, v83
	v_or_b32_e32 v84, 48, v153
	v_add_f32_e32 v82, 1.0, v82
	v_rcp_f32_e32 v85, v82
	v_add_f32_e32 v82, 1.0, v83
	v_rcp_f32_e32 v86, v82
	v_mad_i64_i32 v[82:83], s[30:31], v84, s49, v[146:147]
	v_mul_f32_e32 v78, v78, v85
	v_mul_f32_e32 v78, v78, v70
	v_mul_f32_e32 v70, v79, v86
	v_mul_f32_e32 v79, 0xbfb8aa3b, v80
	v_exp_f32_e32 v79, v79
	v_mul_f32_e32 v84, 0xbfb8aa3b, v81
	v_exp_f32_e32 v84, v84
	v_mul_f32_e32 v85, v70, v71
	v_add_f32_e32 v70, 1.0, v79
	v_rcp_f32_e32 v70, v70
	v_add_f32_e32 v71, 1.0, v84
	v_mul_f32_e32 v79, 0xbfb8aa3b, v74
	v_rcp_f32_e32 v71, v71
	v_exp_f32_e32 v79, v79
	v_mul_f32_e32 v70, v80, v70
	v_mul_f32_e32 v72, v70, v72
	v_mul_f32_e32 v70, v81, v71
	v_add_f32_e32 v71, 1.0, v79
	v_rcp_f32_e32 v71, v71
	v_mul_f32_e32 v79, 0xbfb8aa3b, v75
	v_mul_f32_e32 v73, v70, v73
	v_exp_f32_e32 v79, v79
	v_mul_f32_e32 v70, v74, v71
	v_mul_f32_e32 v74, v70, v66
	v_mul_f32_e32 v70, 0xbfb8aa3b, v76
	v_exp_f32_e32 v70, v70
	v_mul_f32_e32 v71, 0xbfb8aa3b, v77
	v_exp_f32_e32 v71, v71
	v_add_f32_e32 v66, 1.0, v79
	v_rcp_f32_e32 v66, v66
	v_add_f32_e32 v70, 1.0, v70
	v_rcp_f32_e32 v70, v70
	v_add_f32_e32 v71, 1.0, v71
	v_rcp_f32_e32 v71, v71
	v_mul_f32_e32 v66, v75, v66
	v_mul_f32_e32 v75, v66, v67
	v_mul_f32_e32 v66, v76, v70
	v_mul_f32_e32 v76, v66, v68
	v_mul_f32_e32 v66, v77, v71
	v_mul_f32_e32 v69, v66, v69
	v_lshl_add_u64 v[70:71], v[82:83], 0, v[114:115]
	v_cvt_pk_bf16_f32 v66, v78, v85
	v_cvt_pk_bf16_f32 v67, v72, v73
	v_cvt_pk_bf16_f32 v68, v74, v75
	v_cvt_pk_bf16_f32 v69, v76, v69
	ds_bpermute_b32 v244, v252, v66
	ds_bpermute_b32 v245, v252, v67
	ds_bpermute_b32 v246, v252, v68
	ds_bpermute_b32 v247, v252, v69
	s_waitcnt lgkmcnt(4)
	s_add_u32 s76, s74, 0xac000
	s_addc_u32 s77, s75, 0
	global_store_dwordx4 v253, v[240:243], s[76:77]
	s_nop 1
	v_mul_f32_e32 v66, 0xbfb8aa3b, v62
	v_exp_f32_e32 v66, v66
	v_mul_f32_e32 v67, 0xbfb8aa3b, v63
	v_exp_f32_e32 v67, v67
	v_add_u32_e32 v68, 0x80, v153
	v_add_f32_e32 v66, 1.0, v66
	v_rcp_f32_e32 v69, v66
	v_add_f32_e32 v66, 1.0, v67
	v_rcp_f32_e32 v70, v66
	v_mad_i64_i32 v[66:67], s[30:31], v68, s49, v[146:147]
	v_mul_f32_e32 v62, v62, v69
	v_mul_f32_e32 v62, v62, v54
	v_mul_f32_e32 v54, v63, v70
	v_mul_f32_e32 v63, 0xbfb8aa3b, v64
	v_exp_f32_e32 v63, v63
	v_mul_f32_e32 v68, 0xbfb8aa3b, v65
	v_exp_f32_e32 v68, v68
	v_mul_f32_e32 v69, v54, v55
	v_add_f32_e32 v54, 1.0, v63
	v_rcp_f32_e32 v54, v54
	v_add_f32_e32 v55, 1.0, v68
	v_mul_f32_e32 v63, 0xbfb8aa3b, v58
	v_rcp_f32_e32 v55, v55
	v_exp_f32_e32 v63, v63
	v_mul_f32_e32 v54, v64, v54
	v_mul_f32_e32 v56, v54, v56
	v_mul_f32_e32 v54, v65, v55
	v_add_f32_e32 v55, 1.0, v63
	v_rcp_f32_e32 v55, v55
	v_mul_f32_e32 v63, 0xbfb8aa3b, v59
	v_mul_f32_e32 v57, v54, v57
	v_exp_f32_e32 v63, v63
	v_mul_f32_e32 v54, v58, v55
	v_mul_f32_e32 v58, v54, v50
	v_mul_f32_e32 v54, 0xbfb8aa3b, v60
	v_exp_f32_e32 v54, v54
	v_mul_f32_e32 v55, 0xbfb8aa3b, v61
	v_exp_f32_e32 v55, v55
	v_add_f32_e32 v50, 1.0, v63
	v_rcp_f32_e32 v50, v50
	v_add_f32_e32 v54, 1.0, v54
	v_rcp_f32_e32 v54, v54
	v_add_f32_e32 v55, 1.0, v55
	v_rcp_f32_e32 v55, v55
	v_mul_f32_e32 v50, v59, v50
	v_mul_f32_e32 v59, v50, v51
	v_mul_f32_e32 v50, v60, v54
	v_mul_f32_e32 v60, v50, v52
	v_mul_f32_e32 v50, v61, v55
	v_mul_f32_e32 v53, v50, v53
	v_lshl_add_u64 v[54:55], v[66:67], 0, v[114:115]
	v_cvt_pk_bf16_f32 v50, v62, v69
	v_cvt_pk_bf16_f32 v51, v56, v57
	v_cvt_pk_bf16_f32 v52, v58, v59
	v_cvt_pk_bf16_f32 v53, v60, v53
	ds_bpermute_b32 v240, v252, v50
	ds_bpermute_b32 v241, v252, v51
	ds_bpermute_b32 v242, v252, v52
	ds_bpermute_b32 v243, v252, v53
	s_waitcnt lgkmcnt(4)
	s_add_u32 s76, s74, 0x102000
	s_addc_u32 s77, s75, 0
	global_store_dwordx4 v253, v[244:247], s[76:77]
	s_nop 1
	v_mul_f32_e32 v50, 0xbfb8aa3b, v46
	v_exp_f32_e32 v50, v50
	v_mul_f32_e32 v51, 0xbfb8aa3b, v47
	v_exp_f32_e32 v51, v51
	v_add_u32_e32 v52, 0x90, v153
	v_add_f32_e32 v50, 1.0, v50
	v_rcp_f32_e32 v53, v50
	v_add_f32_e32 v50, 1.0, v51
	v_rcp_f32_e32 v54, v50
	v_mad_i64_i32 v[50:51], s[30:31], v52, s49, v[146:147]
	v_mul_f32_e32 v46, v46, v53
	v_mul_f32_e32 v46, v46, v38
	v_mul_f32_e32 v38, v47, v54
	v_mul_f32_e32 v47, 0xbfb8aa3b, v48
	v_exp_f32_e32 v47, v47
	v_mul_f32_e32 v52, 0xbfb8aa3b, v49
	v_exp_f32_e32 v52, v52
	v_mul_f32_e32 v53, v38, v39
	v_add_f32_e32 v38, 1.0, v47
	v_rcp_f32_e32 v38, v38
	v_add_f32_e32 v39, 1.0, v52
	v_mul_f32_e32 v47, 0xbfb8aa3b, v42
	v_rcp_f32_e32 v39, v39
	v_exp_f32_e32 v47, v47
	v_mul_f32_e32 v38, v48, v38
	v_mul_f32_e32 v40, v38, v40
	v_mul_f32_e32 v38, v49, v39
	v_add_f32_e32 v39, 1.0, v47
	v_rcp_f32_e32 v39, v39
	v_mul_f32_e32 v47, 0xbfb8aa3b, v43
	v_mul_f32_e32 v41, v38, v41
	v_exp_f32_e32 v47, v47
	v_mul_f32_e32 v38, v42, v39
	v_mul_f32_e32 v42, v38, v34
	v_mul_f32_e32 v38, 0xbfb8aa3b, v44
	v_exp_f32_e32 v38, v38
	v_mul_f32_e32 v39, 0xbfb8aa3b, v45
	v_exp_f32_e32 v39, v39
	v_add_f32_e32 v34, 1.0, v47
	v_rcp_f32_e32 v34, v34
	v_add_f32_e32 v38, 1.0, v38
	v_rcp_f32_e32 v38, v38
	v_add_f32_e32 v39, 1.0, v39
	v_rcp_f32_e32 v39, v39
	v_mul_f32_e32 v34, v43, v34
	v_mul_f32_e32 v43, v34, v35
	v_mul_f32_e32 v34, v44, v38
	v_mul_f32_e32 v44, v34, v36
	v_mul_f32_e32 v34, v45, v39
	v_mul_f32_e32 v37, v34, v37
	v_lshl_add_u64 v[38:39], v[50:51], 0, v[114:115]
	v_cvt_pk_bf16_f32 v34, v46, v53
	v_cvt_pk_bf16_f32 v35, v40, v41
	v_cvt_pk_bf16_f32 v36, v42, v43
	v_cvt_pk_bf16_f32 v37, v44, v37
	ds_bpermute_b32 v244, v252, v34
	ds_bpermute_b32 v245, v252, v35
	ds_bpermute_b32 v246, v252, v36
	ds_bpermute_b32 v247, v252, v37
	s_waitcnt lgkmcnt(4)
; __device__ __forceinline__ unsigned cvt_pk_bf16(float lo, float hi) { unsigned r; asm volatile("v_cvt_pk_bf16_f32 %0, %1, %2" : "=v"(r) : "v"(lo), "v"(hi)); return r; }
; __device__ __forceinline__ float sigmoid_f(float x) { return __builtin_amdgcn_rcpf(1.0f + __builtin_amdgcn_exp2f(-1.4426950408889634f * x)); }
;     __device__ __forceinline__ void operator()(const f32x4 (&acc)[2][2][4][2], const Unit& u, int wr, int wc, int fr, int fq) const {
;         const int row0 = u.pm * BM + wr * 64 + fr, col0 = u.pn * HALF + wc * 32 + 8 * fq;
; #pragma unroll
;         for (int ai = 0; ai < 2; ++ai)
; #pragma unroll
;             for (int m = 0; m < 4; ++m) { bf16_t* rowp = ACT + (size_t)(row0 + ai * HALF + m * 16) * ldc + col0;
;                 float v[8];
; #pragma unroll
;                 for (int n = 0; n < 2; ++n)
; #pragma unroll
;                     for (int j = 0; j < 4; ++j) { const float g = acc[ai][0][m][n][j], up = acc[ai][1][m][n][j]; v[4 * n + j] = g * sigmoid_f(g) * up; }
;                 u32x4 w; w.x = cvt_pk_bf16(v[0], v[1]); w.y = cvt_pk_bf16(v[2], v[3]); w.z = cvt_pk_bf16(v[4], v[5]); w.w = cvt_pk_bf16(v[6], v[7]);
;                 *(u32x4*)rowp = w; }
	s_add_u32 s76, s74, 0x2b0000
	s_addc_u32 s77, s75, 0
	global_store_dwordx4 v253, v[240:243], s[76:77]
	s_nop 1
	v_mul_f32_e32 v34, 0xbfb8aa3b, v30
	v_exp_f32_e32 v34, v34
	v_mul_f32_e32 v35, 0xbfb8aa3b, v31
	v_exp_f32_e32 v35, v35
	v_add_u32_e32 v36, 0xa0, v153
	v_add_f32_e32 v34, 1.0, v34
	v_rcp_f32_e32 v37, v34
	v_add_f32_e32 v34, 1.0, v35
	v_rcp_f32_e32 v38, v34
	v_mad_i64_i32 v[34:35], s[30:31], v36, s49, v[146:147]
	v_mul_f32_e32 v30, v30, v37
	v_mul_f32_e32 v30, v30, v22
	v_mul_f32_e32 v22, v31, v38
	v_mul_f32_e32 v31, 0xbfb8aa3b, v32
	v_exp_f32_e32 v31, v31
	v_mul_f32_e32 v36, 0xbfb8aa3b, v33
	v_exp_f32_e32 v36, v36
	v_mul_f32_e32 v37, v22, v23
	v_add_f32_e32 v22, 1.0, v31
	v_rcp_f32_e32 v22, v22
	v_add_f32_e32 v23, 1.0, v36
	v_mul_f32_e32 v31, 0xbfb8aa3b, v26
	v_rcp_f32_e32 v23, v23
	v_exp_f32_e32 v31, v31
	v_mul_f32_e32 v22, v32, v22
	v_mul_f32_e32 v24, v22, v24
	v_mul_f32_e32 v22, v33, v23
	v_add_f32_e32 v23, 1.0, v31
	v_rcp_f32_e32 v23, v23
	v_mul_f32_e32 v31, 0xbfb8aa3b, v27
	v_mul_f32_e32 v25, v22, v25
	v_exp_f32_e32 v31, v31
	v_mul_f32_e32 v22, v26, v23
	v_mul_f32_e32 v26, v22, v18
	v_mul_f32_e32 v22, 0xbfb8aa3b, v28
	v_exp_f32_e32 v22, v22
	v_mul_f32_e32 v23, 0xbfb8aa3b, v29
	v_exp_f32_e32 v23, v23
	v_add_f32_e32 v18, 1.0, v31
	v_rcp_f32_e32 v18, v18
	v_add_f32_e32 v22, 1.0, v22
	v_rcp_f32_e32 v22, v22
	v_add_f32_e32 v23, 1.0, v23
	v_rcp_f32_e32 v23, v23
	v_mul_f32_e32 v18, v27, v18
	v_mul_f32_e32 v27, v18, v19
	v_mul_f32_e32 v18, v28, v22
	v_mul_f32_e32 v28, v18, v20
	v_mul_f32_e32 v18, v29, v23
	v_mul_f32_e32 v21, v18, v21
	v_lshl_add_u64 v[22:23], v[34:35], 0, v[114:115]
	v_cvt_pk_bf16_f32 v18, v30, v37
	v_cvt_pk_bf16_f32 v19, v24, v25
	v_cvt_pk_bf16_f32 v20, v26, v27
	v_cvt_pk_bf16_f32 v21, v28, v21
	ds_bpermute_b32 v240, v252, v18
	ds_bpermute_b32 v241, v252, v19
	ds_bpermute_b32 v242, v252, v20
	ds_bpermute_b32 v243, v252, v21
	s_waitcnt lgkmcnt(4)
	s_add_u32 s76, s74, 0x306000
	s_addc_u32 s77, s75, 0
	global_store_dwordx4 v253, v[244:247], s[76:77]
	s_nop 1
	v_mul_f32_e32 v18, 0xbfb8aa3b, v14
	v_exp_f32_e32 v18, v18
	v_mul_f32_e32 v19, 0xbfb8aa3b, v15
	v_exp_f32_e32 v19, v19
	v_add_u32_e32 v20, 0xb0, v153
	v_add_f32_e32 v18, 1.0, v18
	v_rcp_f32_e32 v21, v18
	v_add_f32_e32 v18, 1.0, v19
	v_rcp_f32_e32 v22, v18
	v_mad_i64_i32 v[18:19], s[30:31], v20, s49, v[146:147]
	v_mul_f32_e32 v14, v14, v21
	v_mul_f32_e32 v14, v14, v6
	v_mul_f32_e32 v6, v15, v22
	v_mul_f32_e32 v15, 0xbfb8aa3b, v16
	v_exp_f32_e32 v15, v15
	v_mul_f32_e32 v20, 0xbfb8aa3b, v17
	v_exp_f32_e32 v20, v20
	v_mul_f32_e32 v21, v6, v7
	v_add_f32_e32 v6, 1.0, v15
	v_rcp_f32_e32 v6, v6
	v_add_f32_e32 v7, 1.0, v20
	v_mul_f32_e32 v15, 0xbfb8aa3b, v10
	v_rcp_f32_e32 v7, v7
	v_exp_f32_e32 v15, v15
	v_mul_f32_e32 v6, v16, v6
	v_mul_f32_e32 v8, v6, v8
	v_mul_f32_e32 v6, v17, v7
	v_add_f32_e32 v7, 1.0, v15
	v_rcp_f32_e32 v7, v7
	v_mul_f32_e32 v15, 0xbfb8aa3b, v11
	v_mul_f32_e32 v9, v6, v9
	v_exp_f32_e32 v15, v15
	v_mul_f32_e32 v6, v10, v7
	v_mul_f32_e32 v10, v6, v2
	v_mul_f32_e32 v6, 0xbfb8aa3b, v12
	v_exp_f32_e32 v6, v6
	v_mul_f32_e32 v7, 0xbfb8aa3b, v13
	v_exp_f32_e32 v7, v7
	v_add_f32_e32 v2, 1.0, v15
	v_rcp_f32_e32 v2, v2
	v_add_f32_e32 v6, 1.0, v6
	v_rcp_f32_e32 v6, v6
	v_add_f32_e32 v7, 1.0, v7
	v_rcp_f32_e32 v7, v7
	v_mul_f32_e32 v2, v11, v2
	v_mul_f32_e32 v11, v2, v3
	v_mul_f32_e32 v2, v12, v6
	v_mul_f32_e32 v12, v2, v4
	v_mul_f32_e32 v2, v13, v7
	v_mul_f32_e32 v5, v2, v5
	v_lshl_add_u64 v[6:7], v[18:19], 0, v[114:115]
	v_cvt_pk_bf16_f32 v2, v14, v21
	v_cvt_pk_bf16_f32 v3, v8, v9
	v_cvt_pk_bf16_f32 v4, v10, v11
	v_cvt_pk_bf16_f32 v5, v12, v5
	ds_bpermute_b32 v244, v252, v2
	ds_bpermute_b32 v245, v252, v3
	ds_bpermute_b32 v246, v252, v4
	ds_bpermute_b32 v247, v252, v5
	s_waitcnt lgkmcnt(4)
	s_add_u32 s76, s74, 0x35c000
	s_addc_u32 s77, s75, 0
	global_store_dwordx4 v253, v[240:243], s[76:77]
	s_waitcnt lgkmcnt(0)
	s_add_u32 s76, s74, 0x3b2000
	s_addc_u32 s77, s75, 0
	global_store_dwordx4 v253, v[244:247], s[76:77]
	s_cbranch_vccnz .LBB0_1077
	s_andn2_b64 vcc, exec, s[6:7]
	s_cbranch_vccnz .LBB0_1076
	s_barrier
	s_branch .LBB0_1076

; __device__ __forceinline__ float bf_lo(unsigned w) { return __uint_as_float(w << 16); }
; __device__ __forceinline__ float bf_hi(unsigned w) { return __uint_as_float(w & 0xffff0000u); }
;     __device__ __forceinline__ void operator()(const f32x4 (&acc)[2][2][4][2], const Unit& u, int wr, int wc, int fr, int fq) const {
;         const int row0 = u.pm * BM + wr * 64 + fr, col0 = u.pn * BM + wc * 32 + 4 * fq;
;         typedef unsigned u32x2 __attribute__((ext_vector_type(2)));
;         u32x2 h[2][4][2][2];
; #pragma unroll
;         for (int ai = 0; ai < 2; ++ai)
; #pragma unroll
;             for (int m = 0; m < 4; ++m)
; #pragma unroll
;                 for (int bj = 0; bj < 2; ++bj)
; #pragma unroll
;                     for (int n = 0; n < 2; ++n) h[ai][m][bj][n] = *(const u32x2*)(HB + (size_t)(row0 + ai * HALF + m * 16) * ld + col0 + bj * HALF + n * 16);
; #pragma unroll
;         for (int ai = 0; ai < 2; ++ai)
; #pragma unroll
;             for (int m = 0; m < 4; ++m)
; #pragma unroll
;                 for (int bj = 0; bj < 2; ++bj)
; #pragma unroll
;                     for (int n = 0; n < 2; ++n) { const u32x2 hh = h[ai][m][bj][n];
;                         const f32x4 hv = {bf_lo(hh.x), bf_hi(hh.x), bf_lo(hh.y), bf_hi(hh.y)};
;                         *(f32x4*)(OUT + (size_t)(row0 + ai * HALF + m * 16) * ld + col0 + bj * HALF + n * 16) = hv + acc[ai][bj][m][n]; }
.LBB0_1167:
	s_lshl_b32 s74, s37, 22
	s_lshl_b32 s75, s38, 10
	s_add_u32 s74, s74, s75
	s_addc_u32 s75, 0, 0
	s_add_u32 s74, s74, s62
	s_addc_u32 s75, s75, s63
	v_mbcnt_lo_u32_b32 v250, -1, 0
	v_mbcnt_hi_u32_b32 v250, -1, v250
	v_and_b32_e32 v251, 3, v250
	v_lshrrev_b32_e32 v250, 2, v250
	v_lshl_add_u32 v252, v251, 4, v250
	v_lshlrev_b32_e32 v252, 2, v252
	v_and_b32_e32 v253, 64, v190
	v_add_u32_e32 v253, v253, v250
	v_lshlrev_b32_e32 v253, 14, v253
	v_lshrrev_b32_e32 v250, 5, v192
	v_lshl_add_u32 v253, v250, 7, v253
	v_lshl_add_u32 v253, v251, 4, v253
	v_lshl_add_u32 v142, s37, 8, v190
	v_lshl_or_b32 v144, s38, 8, v192
	v_ashrrev_i32_e32 v145, 31, v144
	v_ashrrev_i32_e32 v143, 31, v142
	v_lshl_add_u64 v[146:147], v[144:145], 1, s[84:85]
	v_lshlrev_b64 v[140:141], 13, v[142:143]
	v_lshl_add_u64 v[140:141], v[146:147], 0, v[140:141]
	global_load_dwordx2 v[196:197], v[140:141], off
	global_load_dwordx2 v[198:199], v[140:141], off offset:32
	global_load_dwordx2 v[200:201], v[140:141], off offset:256
	v_or_b32_e32 v202, 16, v142
	v_ashrrev_i32_e32 v203, 31, v202
	global_load_dwordx2 v[204:205], v[140:141], off offset:288
	v_lshlrev_b64 v[140:141], 13, v[202:203]
	v_lshl_add_u64 v[148:149], v[146:147], 0, v[140:141]
	global_load_dwordx2 v[206:207], v[148:149], off
	global_load_dwordx2 v[208:209], v[148:149], off offset:32
	global_load_dwordx2 v[210:211], v[148:149], off offset:256
	global_load_dwordx2 v[212:213], v[148:149], off offset:288
	v_or_b32_e32 v186, 32, v142
	v_or_b32_e32 v176, 48, v142
	v_add_u32_e32 v168, 0x80, v142
	v_add_u32_e32 v158, 0x90, v142
	v_add_u32_e32 v150, 0xa0, v142
	v_add_u32_e32 v140, 0xb0, v142
	v_ashrrev_i32_e32 v187, 31, v186
	v_ashrrev_i32_e32 v177, 31, v176
	v_ashrrev_i32_e32 v169, 31, v168
	v_ashrrev_i32_e32 v159, 31, v158
	v_ashrrev_i32_e32 v151, 31, v150
	v_ashrrev_i32_e32 v141, 31, v140
	v_lshlrev_b64 v[142:143], 14, v[142:143]
	v_lshlrev_b64 v[152:153], 13, v[186:187]
	v_lshlrev_b64 v[154:155], 13, v[176:177]
	v_lshlrev_b64 v[156:157], 13, v[168:169]
	v_lshlrev_b64 v[160:161], 13, v[158:159]
	v_lshlrev_b64 v[162:163], 13, v[150:151]
	v_lshlrev_b64 v[144:145], 2, v[144:145]
	v_lshlrev_b64 v[164:165], 13, v[140:141]
	v_lshl_add_u64 v[142:143], s[62:63], 0, v[142:143]
	v_lshl_add_u64 v[152:153], v[146:147], 0, v[152:153]
	v_lshl_add_u64 v[154:155], v[146:147], 0, v[154:155]
	v_lshl_add_u64 v[156:157], v[146:147], 0, v[156:157]
	v_lshl_add_u64 v[160:161], v[146:147], 0, v[160:161]
	v_lshl_add_u64 v[148:149], v[146:147], 0, v[162:163]
	v_lshl_add_u64 v[214:215], v[146:147], 0, v[164:165]
	v_lshl_add_u64 v[216:217], v[142:143], 0, v[144:145]
	global_load_dwordx2 v[218:219], v[152:153], off
	global_load_dwordx2 v[220:221], v[152:153], off offset:32
	global_load_dwordx2 v[222:223], v[152:153], off offset:256
	global_load_dwordx2 v[224:225], v[152:153], off offset:288
	global_load_dwordx2 v[226:227], v[154:155], off
	global_load_dwordx2 v[228:229], v[154:155], off offset:32
	global_load_dwordx2 v[188:189], v[154:155], off offset:256
	global_load_dwordx2 v[184:185], v[154:155], off offset:288
	global_load_dwordx2 v[182:183], v[156:157], off
	global_load_dwordx2 v[180:181], v[156:157], off offset:32
	global_load_dwordx2 v[178:179], v[156:157], off offset:256
	global_load_dwordx2 v[174:175], v[156:157], off offset:288
	global_load_dwordx2 v[172:173], v[160:161], off
	global_load_dwordx2 v[170:171], v[160:161], off offset:32
	global_load_dwordx2 v[166:167], v[160:161], off offset:256
	global_load_dwordx2 v[164:165], v[160:161], off offset:288
	global_load_dwordx2 v[162:163], v[148:149], off
	s_nop 0
	global_load_dwordx2 v[160:161], v[148:149], off offset:32
	global_load_dwordx2 v[156:157], v[148:149], off offset:256
	global_load_dwordx2 v[154:155], v[148:149], off offset:288
	global_load_dwordx2 v[152:153], v[214:215], off
	s_nop 0
	global_load_dwordx2 v[148:149], v[214:215], off offset:32
	global_load_dwordx2 v[146:147], v[214:215], off offset:256
	global_load_dwordx2 v[142:143], v[214:215], off offset:288
	s_and_b64 vcc, exec, s[0:1]
	s_mov_b64 s[0:1], -1
	s_waitcnt vmcnt(0)
	v_lshlrev_b32_e32 v214, 16, v196
	v_and_b32_e32 v215, 0xffff0000, v196
	v_lshlrev_b32_e32 v196, 16, v197
	v_and_b32_e32 v197, 0xffff0000, v197
	v_lshlrev_b32_e32 v230, 16, v198
	v_and_b32_e32 v231, 0xffff0000, v198
	v_lshlrev_b32_e32 v198, 16, v199
	v_and_b32_e32 v199, 0xffff0000, v199
	v_pk_add_f32 v[126:127], v[126:127], v[196:197]
	v_pk_add_f32 v[124:125], v[124:125], v[214:215]
	v_pk_add_f32 v[120:121], v[120:121], v[230:231]
	v_lshlrev_b32_e32 v232, 16, v200
	v_and_b32_e32 v233, 0xffff0000, v200
	v_pk_add_f32 v[122:123], v[122:123], v[198:199]
	ds_bpermute_b32 v240, v252, v124
	ds_bpermute_b32 v241, v252, v125
	ds_bpermute_b32 v242, v252, v126
	ds_bpermute_b32 v243, v252, v127
	ds_bpermute_b32 v244, v252, v120
	ds_bpermute_b32 v245, v252, v121
	ds_bpermute_b32 v246, v252, v122
	ds_bpermute_b32 v247, v252, v123
	s_waitcnt lgkmcnt(4)
	s_mov_b64 s[76:77], s[74:75]
	global_store_dwordx4 v253, v[240:243], s[76:77]
	v_pk_add_f32 v[116:117], v[116:117], v[232:233]
	s_nop 0
	v_lshlrev_b32_e32 v120, 16, v201
	v_and_b32_e32 v121, 0xffff0000, v201
	v_pk_add_f32 v[118:119], v[118:119], v[120:121]
	ds_bpermute_b32 v240, v252, v116
	ds_bpermute_b32 v241, v252, v117
	ds_bpermute_b32 v242, v252, v118
	ds_bpermute_b32 v243, v252, v119
	s_waitcnt lgkmcnt(4)
	global_store_dwordx4 v253, v[244:247], s[76:77] offset:64
	s_nop 1
	v_lshlrev_b32_e32 v116, 16, v204
	v_and_b32_e32 v117, 0xffff0000, v204
	v_lshlrev_b32_e32 v118, 16, v205
	v_and_b32_e32 v119, 0xffff0000, v205
	v_pk_add_f32 v[110:111], v[110:111], v[118:119]
	v_pk_add_f32 v[108:109], v[108:109], v[116:117]
	ds_bpermute_b32 v244, v252, v108
	ds_bpermute_b32 v245, v252, v109
	ds_bpermute_b32 v246, v252, v110
	ds_bpermute_b32 v247, v252, v111
	s_waitcnt lgkmcnt(4)
; __device__ __forceinline__ float bf_lo(unsigned w) { return __uint_as_float(w << 16); }
; __device__ __forceinline__ float bf_hi(unsigned w) { return __uint_as_float(w & 0xffff0000u); }
;     __device__ __forceinline__ void operator()(const f32x4 (&acc)[2][2][4][2], const Unit& u, int wr, int wc, int fr, int fq) const {
;         const int row0 = u.pm * BM + wr * 64 + fr, col0 = u.pn * BM + wc * 32 + 4 * fq;
;         typedef unsigned u32x2 __attribute__((ext_vector_type(2)));
;         u32x2 h[2][4][2][2];
; #pragma unroll
;         for (int ai = 0; ai < 2; ++ai)
; #pragma unroll
;             for (int m = 0; m < 4; ++m)
; #pragma unroll
;                 for (int bj = 0; bj < 2; ++bj)
; #pragma unroll
;                     for (int n = 0; n < 2; ++n) h[ai][m][bj][n] = *(const u32x2*)(HB + (size_t)(row0 + ai * HALF + m * 16) * ld + col0 + bj * HALF + n * 16);
; #pragma unroll
;         for (int ai = 0; ai < 2; ++ai)
; #pragma unroll
;             for (int m = 0; m < 4; ++m)
; #pragma unroll
;                 for (int bj = 0; bj < 2; ++bj)
; #pragma unroll
;                     for (int n = 0; n < 2; ++n) { const u32x2 hh = h[ai][m][bj][n];
;                         const f32x4 hv = {bf_lo(hh.x), bf_hi(hh.x), bf_lo(hh.y), bf_hi(hh.y)};
;                         *(f32x4*)(OUT + (size_t)(row0 + ai * HALF + m * 16) * ld + col0 + bj * HALF + n * 16) = hv + acc[ai][bj][m][n]; }
	global_store_dwordx4 v253, v[240:243], s[76:77] offset:512
	s_nop 1
	v_lshlrev_b32_e32 v108, 16, v206
	v_and_b32_e32 v109, 0xffff0000, v206
	v_pk_add_f32 v[108:109], v[112:113], v[108:109]
	v_lshlrev_b64 v[112:113], 14, v[202:203]
	v_lshlrev_b32_e32 v110, 16, v207
	v_and_b32_e32 v111, 0xffff0000, v207
	v_lshl_add_u64 v[112:113], s[62:63], 0, v[112:113]
	v_pk_add_f32 v[110:111], v[114:115], v[110:111]
	v_lshl_add_u64 v[112:113], v[112:113], 0, v[144:145]
	ds_bpermute_b32 v240, v252, v108
	ds_bpermute_b32 v241, v252, v109
	ds_bpermute_b32 v242, v252, v110
	ds_bpermute_b32 v243, v252, v111
	s_waitcnt lgkmcnt(4)
	global_store_dwordx4 v253, v[244:247], s[76:77] offset:576
	s_nop 1
	v_lshlrev_b32_e32 v108, 16, v208
	v_and_b32_e32 v109, 0xffff0000, v208
	v_lshlrev_b32_e32 v110, 16, v209
	v_and_b32_e32 v111, 0xffff0000, v209
	v_pk_add_f32 v[106:107], v[106:107], v[110:111]
	v_pk_add_f32 v[104:105], v[104:105], v[108:109]
	ds_bpermute_b32 v244, v252, v104
	ds_bpermute_b32 v245, v252, v105
	ds_bpermute_b32 v246, v252, v106
	ds_bpermute_b32 v247, v252, v107
	s_waitcnt lgkmcnt(4)
	s_add_u32 s76, s74, 0x40000
	s_addc_u32 s77, s75, 0
	global_store_dwordx4 v253, v[240:243], s[76:77]
	s_nop 1
	v_lshlrev_b32_e32 v104, 16, v210
	v_and_b32_e32 v105, 0xffff0000, v210
	v_lshlrev_b32_e32 v106, 16, v211
	v_and_b32_e32 v107, 0xffff0000, v211
	v_pk_add_f32 v[102:103], v[102:103], v[106:107]
	v_pk_add_f32 v[100:101], v[100:101], v[104:105]
	ds_bpermute_b32 v240, v252, v100
	ds_bpermute_b32 v241, v252, v101
	ds_bpermute_b32 v242, v252, v102
	ds_bpermute_b32 v243, v252, v103
	s_waitcnt lgkmcnt(4)
	global_store_dwordx4 v253, v[244:247], s[76:77] offset:64
	s_nop 1
	v_lshlrev_b32_e32 v100, 16, v212
	v_and_b32_e32 v101, 0xffff0000, v212
	v_lshlrev_b32_e32 v102, 16, v213
	v_and_b32_e32 v103, 0xffff0000, v213
	v_pk_add_f32 v[94:95], v[94:95], v[102:103]
	v_pk_add_f32 v[92:93], v[92:93], v[100:101]
	ds_bpermute_b32 v244, v252, v92
	ds_bpermute_b32 v245, v252, v93
	ds_bpermute_b32 v246, v252, v94
	ds_bpermute_b32 v247, v252, v95
	s_waitcnt lgkmcnt(4)
	global_store_dwordx4 v253, v[240:243], s[76:77] offset:512
	s_nop 1
	v_lshlrev_b32_e32 v92, 16, v218
	v_and_b32_e32 v93, 0xffff0000, v218
	v_pk_add_f32 v[92:93], v[96:97], v[92:93]
	v_lshlrev_b64 v[96:97], 14, v[186:187]
	v_lshlrev_b32_e32 v94, 16, v219
	v_and_b32_e32 v95, 0xffff0000, v219
	v_lshl_add_u64 v[96:97], s[62:63], 0, v[96:97]
	v_pk_add_f32 v[94:95], v[98:99], v[94:95]
	v_lshl_add_u64 v[96:97], v[96:97], 0, v[144:145]
	ds_bpermute_b32 v240, v252, v92
	ds_bpermute_b32 v241, v252, v93
	ds_bpermute_b32 v242, v252, v94
	ds_bpermute_b32 v243, v252, v95
	s_waitcnt lgkmcnt(4)
	global_store_dwordx4 v253, v[244:247], s[76:77] offset:576
	s_nop 1
	v_lshlrev_b32_e32 v92, 16, v220
	v_and_b32_e32 v93, 0xffff0000, v220
	v_lshlrev_b32_e32 v94, 16, v221
	v_and_b32_e32 v95, 0xffff0000, v221
	v_pk_add_f32 v[90:91], v[90:91], v[94:95]
	v_pk_add_f32 v[88:89], v[88:89], v[92:93]
	ds_bpermute_b32 v244, v252, v88
	ds_bpermute_b32 v245, v252, v89
	ds_bpermute_b32 v246, v252, v90
	ds_bpermute_b32 v247, v252, v91
	s_waitcnt lgkmcnt(4)
	s_add_u32 s76, s74, 0x80000
	s_addc_u32 s77, s75, 0
	global_store_dwordx4 v253, v[240:243], s[76:77]
	s_nop 1
	v_lshlrev_b32_e32 v88, 16, v222
	v_and_b32_e32 v89, 0xffff0000, v222
	v_lshlrev_b32_e32 v90, 16, v223
	v_and_b32_e32 v91, 0xffff0000, v223
	v_pk_add_f32 v[86:87], v[86:87], v[90:91]
	v_pk_add_f32 v[84:85], v[84:85], v[88:89]
	ds_bpermute_b32 v240, v252, v84
	ds_bpermute_b32 v241, v252, v85
	ds_bpermute_b32 v242, v252, v86
	ds_bpermute_b32 v243, v252, v87
	s_waitcnt lgkmcnt(4)
	global_store_dwordx4 v253, v[244:247], s[76:77] offset:64
	s_nop 1
	v_lshlrev_b32_e32 v84, 16, v224
	v_and_b32_e32 v85, 0xffff0000, v224
	v_lshlrev_b32_e32 v86, 16, v225
	v_and_b32_e32 v87, 0xffff0000, v225
	v_pk_add_f32 v[78:79], v[78:79], v[86:87]
	v_pk_add_f32 v[76:77], v[76:77], v[84:85]
	ds_bpermute_b32 v244, v252, v76
	ds_bpermute_b32 v245, v252, v77
	ds_bpermute_b32 v246, v252, v78
	ds_bpermute_b32 v247, v252, v79
	s_waitcnt lgkmcnt(4)
	global_store_dwordx4 v253, v[240:243], s[76:77] offset:512
	s_nop 1
	v_lshlrev_b32_e32 v76, 16, v226
	v_and_b32_e32 v77, 0xffff0000, v226
	v_pk_add_f32 v[76:77], v[80:81], v[76:77]
	v_lshlrev_b64 v[80:81], 14, v[176:177]
	v_lshlrev_b32_e32 v78, 16, v227
	v_and_b32_e32 v79, 0xffff0000, v227
	v_lshl_add_u64 v[80:81], s[62:63], 0, v[80:81]
	v_pk_add_f32 v[78:79], v[82:83], v[78:79]
	v_lshl_add_u64 v[80:81], v[80:81], 0, v[144:145]
	ds_bpermute_b32 v240, v252, v76
	ds_bpermute_b32 v241, v252, v77
	ds_bpermute_b32 v242, v252, v78
	ds_bpermute_b32 v243, v252, v79
	s_waitcnt lgkmcnt(4)
	global_store_dwordx4 v253, v[244:247], s[76:77] offset:576
	s_nop 1
	v_lshlrev_b32_e32 v76, 16, v228
	v_and_b32_e32 v77, 0xffff0000, v228
	v_lshlrev_b32_e32 v78, 16, v229
	v_and_b32_e32 v79, 0xffff0000, v229
	v_pk_add_f32 v[74:75], v[74:75], v[78:79]
	v_pk_add_f32 v[72:73], v[72:73], v[76:77]
	ds_bpermute_b32 v244, v252, v72
	ds_bpermute_b32 v245, v252, v73
	ds_bpermute_b32 v246, v252, v74
	ds_bpermute_b32 v247, v252, v75
	s_waitcnt lgkmcnt(4)
	s_add_u32 s76, s74, 0xc0000
	s_addc_u32 s77, s75, 0
	global_store_dwordx4 v253, v[240:243], s[76:77]
	s_nop 1
	v_lshlrev_b32_e32 v72, 16, v188
	v_and_b32_e32 v73, 0xffff0000, v188
	v_lshlrev_b32_e32 v74, 16, v189
	v_and_b32_e32 v75, 0xffff0000, v189
	v_pk_add_f32 v[70:71], v[70:71], v[74:75]
	v_pk_add_f32 v[68:69], v[68:69], v[72:73]
	ds_bpermute_b32 v240, v252, v68
	ds_bpermute_b32 v241, v252, v69
	ds_bpermute_b32 v242, v252, v70
	ds_bpermute_b32 v243, v252, v71
	s_waitcnt lgkmcnt(4)
; __device__ __forceinline__ float bf_lo(unsigned w) { return __uint_as_float(w << 16); }
; __device__ __forceinline__ float bf_hi(unsigned w) { return __uint_as_float(w & 0xffff0000u); }
;     __device__ __forceinline__ void operator()(const f32x4 (&acc)[2][2][4][2], const Unit& u, int wr, int wc, int fr, int fq) const {
;         const int row0 = u.pm * BM + wr * 64 + fr, col0 = u.pn * BM + wc * 32 + 4 * fq;
;         typedef unsigned u32x2 __attribute__((ext_vector_type(2)));
;         u32x2 h[2][4][2][2];
; #pragma unroll
;         for (int ai = 0; ai < 2; ++ai)
; #pragma unroll
;             for (int m = 0; m < 4; ++m)
; #pragma unroll
;                 for (int bj = 0; bj < 2; ++bj)
; #pragma unroll
;                     for (int n = 0; n < 2; ++n) h[ai][m][bj][n] = *(const u32x2*)(HB + (size_t)(row0 + ai * HALF + m * 16) * ld + col0 + bj * HALF + n * 16);
; #pragma unroll
;         for (int ai = 0; ai < 2; ++ai)
; #pragma unroll
;             for (int m = 0; m < 4; ++m)
; #pragma unroll
;                 for (int bj = 0; bj < 2; ++bj)
; #pragma unroll
;                     for (int n = 0; n < 2; ++n) { const u32x2 hh = h[ai][m][bj][n];
;                         const f32x4 hv = {bf_lo(hh.x), bf_hi(hh.x), bf_lo(hh.y), bf_hi(hh.y)};
;                         *(f32x4*)(OUT + (size_t)(row0 + ai * HALF + m * 16) * ld + col0 + bj * HALF + n * 16) = hv + acc[ai][bj][m][n]; }
	global_store_dwordx4 v253, v[244:247], s[76:77] offset:64
	s_nop 1
	v_lshlrev_b32_e32 v68, 16, v184
	v_and_b32_e32 v69, 0xffff0000, v184
	v_lshlrev_b32_e32 v70, 16, v185
	v_and_b32_e32 v71, 0xffff0000, v185
	v_pk_add_f32 v[66:67], v[66:67], v[70:71]
	v_pk_add_f32 v[64:65], v[64:65], v[68:69]
	ds_bpermute_b32 v244, v252, v64
	ds_bpermute_b32 v245, v252, v65
	ds_bpermute_b32 v246, v252, v66
	ds_bpermute_b32 v247, v252, v67
	s_waitcnt lgkmcnt(4)
	global_store_dwordx4 v253, v[240:243], s[76:77] offset:512
	s_nop 1
	v_lshlrev_b32_e32 v64, 16, v182
	v_and_b32_e32 v65, 0xffff0000, v182
	v_pk_add_f32 v[60:61], v[60:61], v[64:65]
	v_lshlrev_b64 v[64:65], 14, v[168:169]
	v_lshlrev_b32_e32 v66, 16, v183
	v_and_b32_e32 v67, 0xffff0000, v183
	v_lshl_add_u64 v[64:65], s[62:63], 0, v[64:65]
	v_pk_add_f32 v[62:63], v[62:63], v[66:67]
	v_lshl_add_u64 v[64:65], v[64:65], 0, v[144:145]
	ds_bpermute_b32 v240, v252, v60
	ds_bpermute_b32 v241, v252, v61
	ds_bpermute_b32 v242, v252, v62
	ds_bpermute_b32 v243, v252, v63
	s_waitcnt lgkmcnt(4)
	global_store_dwordx4 v253, v[244:247], s[76:77] offset:576
	s_nop 1
	v_lshlrev_b32_e32 v60, 16, v180
	v_and_b32_e32 v61, 0xffff0000, v180
	v_lshlrev_b32_e32 v62, 16, v181
	v_and_b32_e32 v63, 0xffff0000, v181
	v_pk_add_f32 v[58:59], v[58:59], v[62:63]
	v_pk_add_f32 v[56:57], v[56:57], v[60:61]
	ds_bpermute_b32 v244, v252, v56
	ds_bpermute_b32 v245, v252, v57
	ds_bpermute_b32 v246, v252, v58
	ds_bpermute_b32 v247, v252, v59
	s_waitcnt lgkmcnt(4)
	s_add_u32 s76, s74, 0x200000
	s_addc_u32 s77, s75, 0
	global_store_dwordx4 v253, v[240:243], s[76:77]
	s_nop 1
	v_lshlrev_b32_e32 v56, 16, v178
	v_and_b32_e32 v57, 0xffff0000, v178
	v_lshlrev_b32_e32 v58, 16, v179
	v_and_b32_e32 v59, 0xffff0000, v179
	v_pk_add_f32 v[54:55], v[54:55], v[58:59]
	v_pk_add_f32 v[52:53], v[52:53], v[56:57]
	ds_bpermute_b32 v240, v252, v52
	ds_bpermute_b32 v241, v252, v53
	ds_bpermute_b32 v242, v252, v54
	ds_bpermute_b32 v243, v252, v55
	s_waitcnt lgkmcnt(4)
	global_store_dwordx4 v253, v[244:247], s[76:77] offset:64
	s_nop 1
	v_lshlrev_b32_e32 v52, 16, v174
	v_and_b32_e32 v53, 0xffff0000, v174
	v_lshlrev_b32_e32 v54, 16, v175
	v_and_b32_e32 v55, 0xffff0000, v175
	v_pk_add_f32 v[46:47], v[46:47], v[54:55]
	v_pk_add_f32 v[44:45], v[44:45], v[52:53]
	ds_bpermute_b32 v244, v252, v44
	ds_bpermute_b32 v245, v252, v45
	ds_bpermute_b32 v246, v252, v46
	ds_bpermute_b32 v247, v252, v47
	s_waitcnt lgkmcnt(4)
	global_store_dwordx4 v253, v[240:243], s[76:77] offset:512
	s_nop 1
	v_lshlrev_b32_e32 v44, 16, v172
	v_and_b32_e32 v45, 0xffff0000, v172
	v_pk_add_f32 v[44:45], v[48:49], v[44:45]
	v_lshlrev_b64 v[48:49], 14, v[158:159]
	v_lshlrev_b32_e32 v46, 16, v173
	v_and_b32_e32 v47, 0xffff0000, v173
	v_lshl_add_u64 v[48:49], s[62:63], 0, v[48:49]
	v_pk_add_f32 v[46:47], v[50:51], v[46:47]
	v_lshl_add_u64 v[48:49], v[48:49], 0, v[144:145]
	ds_bpermute_b32 v240, v252, v44
	ds_bpermute_b32 v241, v252, v45
	ds_bpermute_b32 v242, v252, v46
	ds_bpermute_b32 v243, v252, v47
	s_waitcnt lgkmcnt(4)
	global_store_dwordx4 v253, v[244:247], s[76:77] offset:576
	s_nop 1
	v_lshlrev_b32_e32 v44, 16, v170
	v_and_b32_e32 v45, 0xffff0000, v170
	v_lshlrev_b32_e32 v46, 16, v171
	v_and_b32_e32 v47, 0xffff0000, v171
	v_pk_add_f32 v[42:43], v[42:43], v[46:47]
	v_pk_add_f32 v[40:41], v[40:41], v[44:45]
	ds_bpermute_b32 v244, v252, v40
	ds_bpermute_b32 v245, v252, v41
	ds_bpermute_b32 v246, v252, v42
	ds_bpermute_b32 v247, v252, v43
	s_waitcnt lgkmcnt(4)
	s_add_u32 s76, s74, 0x240000
	s_addc_u32 s77, s75, 0
	global_store_dwordx4 v253, v[240:243], s[76:77]
	s_nop 1
	v_lshlrev_b32_e32 v40, 16, v166
	v_and_b32_e32 v41, 0xffff0000, v166
	v_lshlrev_b32_e32 v42, 16, v167
	v_and_b32_e32 v43, 0xffff0000, v167
	v_pk_add_f32 v[38:39], v[38:39], v[42:43]
	v_pk_add_f32 v[36:37], v[36:37], v[40:41]
	ds_bpermute_b32 v240, v252, v36
	ds_bpermute_b32 v241, v252, v37
	ds_bpermute_b32 v242, v252, v38
	ds_bpermute_b32 v243, v252, v39
	s_waitcnt lgkmcnt(4)
	global_store_dwordx4 v253, v[244:247], s[76:77] offset:64
	s_nop 1
	v_lshlrev_b32_e32 v36, 16, v164
	v_and_b32_e32 v37, 0xffff0000, v164
	v_lshlrev_b32_e32 v38, 16, v165
	v_and_b32_e32 v39, 0xffff0000, v165
	v_pk_add_f32 v[30:31], v[30:31], v[38:39]
	v_pk_add_f32 v[28:29], v[28:29], v[36:37]
	ds_bpermute_b32 v244, v252, v28
	ds_bpermute_b32 v245, v252, v29
	ds_bpermute_b32 v246, v252, v30
	ds_bpermute_b32 v247, v252, v31
	s_waitcnt lgkmcnt(4)
; __device__ __forceinline__ float bf_lo(unsigned w) { return __uint_as_float(w << 16); }
; __device__ __forceinline__ float bf_hi(unsigned w) { return __uint_as_float(w & 0xffff0000u); }
;     __device__ __forceinline__ void operator()(const f32x4 (&acc)[2][2][4][2], const Unit& u, int wr, int wc, int fr, int fq) const {
;         const int row0 = u.pm * BM + wr * 64 + fr, col0 = u.pn * BM + wc * 32 + 4 * fq;
;         typedef unsigned u32x2 __attribute__((ext_vector_type(2)));
;         u32x2 h[2][4][2][2];
; #pragma unroll
;         for (int ai = 0; ai < 2; ++ai)
; #pragma unroll
;             for (int m = 0; m < 4; ++m)
; #pragma unroll
;                 for (int bj = 0; bj < 2; ++bj)
; #pragma unroll
;                     for (int n = 0; n < 2; ++n) h[ai][m][bj][n] = *(const u32x2*)(HB + (size_t)(row0 + ai * HALF + m * 16) * ld + col0 + bj * HALF + n * 16);
; #pragma unroll
;         for (int ai = 0; ai < 2; ++ai)
; #pragma unroll
;             for (int m = 0; m < 4; ++m)
; #pragma unroll
;                 for (int bj = 0; bj < 2; ++bj)
; #pragma unroll
;                     for (int n = 0; n < 2; ++n) { const u32x2 hh = h[ai][m][bj][n];
;                         const f32x4 hv = {bf_lo(hh.x), bf_hi(hh.x), bf_lo(hh.y), bf_hi(hh.y)};
;                         *(f32x4*)(OUT + (size_t)(row0 + ai * HALF + m * 16) * ld + col0 + bj * HALF + n * 16) = hv + acc[ai][bj][m][n]; }
	global_store_dwordx4 v253, v[240:243], s[76:77] offset:512
	s_nop 1
	v_lshlrev_b32_e32 v28, 16, v162
	v_and_b32_e32 v29, 0xffff0000, v162
	v_pk_add_f32 v[28:29], v[32:33], v[28:29]
	v_lshlrev_b64 v[32:33], 14, v[150:151]
	v_lshlrev_b32_e32 v30, 16, v163
	v_and_b32_e32 v31, 0xffff0000, v163
	v_lshl_add_u64 v[32:33], s[62:63], 0, v[32:33]
	v_pk_add_f32 v[30:31], v[34:35], v[30:31]
	v_lshl_add_u64 v[32:33], v[32:33], 0, v[144:145]
	ds_bpermute_b32 v240, v252, v28
	ds_bpermute_b32 v241, v252, v29
	ds_bpermute_b32 v242, v252, v30
	ds_bpermute_b32 v243, v252, v31
	s_waitcnt lgkmcnt(4)
	global_store_dwordx4 v253, v[244:247], s[76:77] offset:576
	s_nop 1
	v_lshlrev_b32_e32 v28, 16, v160
	v_and_b32_e32 v29, 0xffff0000, v160
	v_lshlrev_b32_e32 v30, 16, v161
	v_and_b32_e32 v31, 0xffff0000, v161
	v_pk_add_f32 v[26:27], v[26:27], v[30:31]
	v_pk_add_f32 v[24:25], v[24:25], v[28:29]
	ds_bpermute_b32 v244, v252, v24
	ds_bpermute_b32 v245, v252, v25
	ds_bpermute_b32 v246, v252, v26
	ds_bpermute_b32 v247, v252, v27
	s_waitcnt lgkmcnt(4)
	s_add_u32 s76, s74, 0x280000
	s_addc_u32 s77, s75, 0
	global_store_dwordx4 v253, v[240:243], s[76:77]
	s_nop 1
	v_lshlrev_b32_e32 v24, 16, v156
	v_and_b32_e32 v25, 0xffff0000, v156
	v_lshlrev_b32_e32 v26, 16, v157
	v_and_b32_e32 v27, 0xffff0000, v157
	v_pk_add_f32 v[22:23], v[22:23], v[26:27]
	v_pk_add_f32 v[20:21], v[20:21], v[24:25]
	ds_bpermute_b32 v240, v252, v20
	ds_bpermute_b32 v241, v252, v21
	ds_bpermute_b32 v242, v252, v22
	ds_bpermute_b32 v243, v252, v23
	s_waitcnt lgkmcnt(4)
	global_store_dwordx4 v253, v[244:247], s[76:77] offset:64
	s_nop 1
	v_lshlrev_b32_e32 v20, 16, v154
	v_and_b32_e32 v21, 0xffff0000, v154
	v_lshlrev_b32_e32 v22, 16, v155
	v_and_b32_e32 v23, 0xffff0000, v155
	v_pk_add_f32 v[14:15], v[14:15], v[22:23]
	v_pk_add_f32 v[12:13], v[12:13], v[20:21]
	ds_bpermute_b32 v244, v252, v12
	ds_bpermute_b32 v245, v252, v13
	ds_bpermute_b32 v246, v252, v14
	ds_bpermute_b32 v247, v252, v15
	s_waitcnt lgkmcnt(4)
	global_store_dwordx4 v253, v[240:243], s[76:77] offset:512
	s_nop 1
	v_lshlrev_b32_e32 v12, 16, v152
	v_and_b32_e32 v13, 0xffff0000, v152
	v_pk_add_f32 v[12:13], v[16:17], v[12:13]
	v_lshlrev_b64 v[16:17], 14, v[140:141]
	v_lshlrev_b32_e32 v14, 16, v153
	v_and_b32_e32 v15, 0xffff0000, v153
	v_lshl_add_u64 v[16:17], s[62:63], 0, v[16:17]
	v_pk_add_f32 v[14:15], v[18:19], v[14:15]
	v_lshl_add_u64 v[16:17], v[16:17], 0, v[144:145]
	ds_bpermute_b32 v240, v252, v12
	ds_bpermute_b32 v241, v252, v13
	ds_bpermute_b32 v242, v252, v14
	ds_bpermute_b32 v243, v252, v15
	s_waitcnt lgkmcnt(4)
	global_store_dwordx4 v253, v[244:247], s[76:77] offset:576
	s_nop 1
	v_lshlrev_b32_e32 v12, 16, v148
	v_and_b32_e32 v13, 0xffff0000, v148
	v_lshlrev_b32_e32 v14, 16, v149
	v_and_b32_e32 v15, 0xffff0000, v149
	v_pk_add_f32 v[10:11], v[10:11], v[14:15]
	v_pk_add_f32 v[8:9], v[8:9], v[12:13]
	ds_bpermute_b32 v244, v252, v8
	ds_bpermute_b32 v245, v252, v9
	ds_bpermute_b32 v246, v252, v10
	ds_bpermute_b32 v247, v252, v11
	s_waitcnt lgkmcnt(4)
	s_add_u32 s76, s74, 0x2c0000
	s_addc_u32 s77, s75, 0
	global_store_dwordx4 v253, v[240:243], s[76:77]
	s_nop 1
	v_lshlrev_b32_e32 v8, 16, v146
	v_and_b32_e32 v9, 0xffff0000, v146
	v_lshlrev_b32_e32 v10, 16, v147
	v_and_b32_e32 v11, 0xffff0000, v147
	v_pk_add_f32 v[6:7], v[6:7], v[10:11]
	v_pk_add_f32 v[4:5], v[4:5], v[8:9]
	ds_bpermute_b32 v240, v252, v4
	ds_bpermute_b32 v241, v252, v5
	ds_bpermute_b32 v242, v252, v6
	ds_bpermute_b32 v243, v252, v7
	s_waitcnt lgkmcnt(4)
	global_store_dwordx4 v253, v[244:247], s[76:77] offset:64
	s_nop 1
	v_lshlrev_b32_e32 v4, 16, v142
	v_and_b32_e32 v5, 0xffff0000, v142
	v_lshlrev_b32_e32 v6, 16, v143
	v_and_b32_e32 v7, 0xffff0000, v143
	v_pk_add_f32 v[2:3], v[2:3], v[6:7]
	v_pk_add_f32 v[0:1], v[0:1], v[4:5]
	ds_bpermute_b32 v244, v252, v0
	ds_bpermute_b32 v245, v252, v1
	ds_bpermute_b32 v246, v252, v2
	ds_bpermute_b32 v247, v252, v3
	s_waitcnt lgkmcnt(4)
	global_store_dwordx4 v253, v[240:243], s[76:77] offset:512
	s_waitcnt lgkmcnt(0)
	global_store_dwordx4 v253, v[244:247], s[76:77] offset:576
	s_cbranch_vccnz .LBB0_1152
	s_andn2_b64 vcc, exec, s[6:7]
	s_cbranch_vccnz .LBB0_1151
	s_barrier
	s_branch .LBB0_1151
